# EpiRes epilogue stores widened to dwordx4 with v_permlane16_swap (strategy 7.3)
# speedup vs baseline: 1.0699x; 1.0053x over previous
;     __device__ __forceinline__ void operator()(const f32x4 (&acc)[2][2][4][2], const Unit& u, int wr, int wc, int fr, int fq) const {
;         const int row0 = u.pm * BM + wr * 64 + fr, col0 = u.pn * BM + wc * 32 + 4 * fq;
; #pragma unroll
;         for (int ai = 0; ai < 2; ++ai) {
;             u32x2e hw[4][2][2], pw[4][2][2]; float scv[4];
; #pragma unroll
;             for (int m = 0; m < 4; ++m) { const int row = row0 + ai * HALF + m * 16; const size_t ro = (size_t)row * 2048 + col0;
;                 scv[m] = GATE ? rss_in[row] : 0.f;
; #pragma unroll
;                 for (int bj = 0; bj < 2; ++bj)
; #pragma unroll
;                     for (int n = 0; n < 2; ++n) { const size_t p = ro + bj * HALF + n * 16; hw[m][bj][n] = *(const u32x2e*)(Hin + p); if (GATE) pw[m][bj][n] = *(const u32x2e*)(PP + p); else pw[m][bj][n] = (u32x2e){0u, 0u}; } }
.Lepi3_noalign:
	s_waitcnt vmcnt(0)
	s_barrier
	v_lshlrev_b32_e32 v130, 9, v235
	v_lshrrev_b32_e32 v131, 3, v237
	v_and_b32_e32 v132, 15, v235
	v_xor_b32_e32 v131, v131, v132
	v_lshl_add_u32 v130, v131, 4, v130
	v_bfe_u32 v131, v237, 2, 1
	v_lshl_add_u32 v130, v131, 3, v130
	v_xor_b32_e32 v131, 32, v130
	v_add_u32_e32 v132, 0x10000, v130
	v_add_u32_e32 v133, 0x10000, v131
	v_lshrrev_b32_e32 v134, 5, v216
	v_and_b32_e32 v135, 31, v216
	v_xor_b32_e32 v135, v135, v134
	v_lshlrev_b32_e32 v135, 4, v135
	v_lshl_or_b32 v134, v134, 12, v135
	v_lshrrev_b32_e32 v135, 6, v183
	s_nop 0
	v_readfirstlane_b32 s7, v135
	s_lshl_b32 s8, s4, 20
	s_lshl_b32 s9, s6, 9
	s_add_i32 s8, s8, s9
	s_lshl_b32 s9, s7, 16
	s_add_i32 s8, s8, s9
	s_lshl_b32 s7, s7, 13
	s_add_u32 s10, s46, s8
	s_addc_u32 s11, s47, 0
	s_add_u32 s14, s52, s8
	s_addc_u32 s15, s53, 0
	s_add_i32 m0, s7, 0x0
	s_add_u32 s2, s10, 0x0
	s_addc_u32 s3, s11, 0
	v_xor_b32_e32 v135, 0x0, v134
	global_load_lds_dwordx4 v135, s[2:3]
	s_add_i32 m0, s7, 0x400
	s_add_u32 s2, s10, 0x2000
	s_addc_u32 s3, s11, 0
	v_xor_b32_e32 v135, 0x20, v134
	global_load_lds_dwordx4 v135, s[2:3]
	s_add_i32 m0, s7, 0x800
	s_add_u32 s2, s10, 0x4000
	s_addc_u32 s3, s11, 0
	v_xor_b32_e32 v135, 0x40, v134
	global_load_lds_dwordx4 v135, s[2:3]
	s_add_i32 m0, s7, 0xc00
	s_add_u32 s2, s10, 0x6000
	s_addc_u32 s3, s11, 0
	v_xor_b32_e32 v135, 0x60, v134
	global_load_lds_dwordx4 v135, s[2:3]
	s_add_i32 m0, s7, 0x1000
	s_add_u32 s2, s10, 0x8000
	s_addc_u32 s3, s11, 0
	v_xor_b32_e32 v135, 0x80, v134
	global_load_lds_dwordx4 v135, s[2:3]
	s_add_i32 m0, s7, 0x1400
	s_add_u32 s2, s10, 0xa000
	s_addc_u32 s3, s11, 0
	v_xor_b32_e32 v135, 0xa0, v134
	global_load_lds_dwordx4 v135, s[2:3]
	s_add_i32 m0, s7, 0x1800
	s_add_u32 s2, s10, 0xc000
	s_addc_u32 s3, s11, 0
	v_xor_b32_e32 v135, 0xc0, v134
	global_load_lds_dwordx4 v135, s[2:3]
	s_add_i32 m0, s7, 0x1c00
	s_add_u32 s2, s10, 0xe000
	s_addc_u32 s3, s11, 0
	v_xor_b32_e32 v135, 0xe0, v134
	global_load_lds_dwordx4 v135, s[2:3]
	s_add_i32 m0, s7, 0x10000
	s_add_u32 s2, s14, 0x0
	s_addc_u32 s3, s15, 0
	v_xor_b32_e32 v135, 0x0, v134
	global_load_lds_dwordx4 v135, s[2:3]
	s_add_i32 m0, s7, 0x10400
	s_add_u32 s2, s14, 0x2000
	s_addc_u32 s3, s15, 0
	v_xor_b32_e32 v135, 0x20, v134
	global_load_lds_dwordx4 v135, s[2:3]
	s_add_i32 m0, s7, 0x10800
	s_add_u32 s2, s14, 0x4000
	s_addc_u32 s3, s15, 0
	v_xor_b32_e32 v135, 0x40, v134
	global_load_lds_dwordx4 v135, s[2:3]
	s_add_i32 m0, s7, 0x10c00
	s_add_u32 s2, s14, 0x6000
	s_addc_u32 s3, s15, 0
	v_xor_b32_e32 v135, 0x60, v134
	global_load_lds_dwordx4 v135, s[2:3]
	s_add_i32 m0, s7, 0x11000
	s_add_u32 s2, s14, 0x8000
	s_addc_u32 s3, s15, 0
	v_xor_b32_e32 v135, 0x80, v134
	global_load_lds_dwordx4 v135, s[2:3]
	s_add_i32 m0, s7, 0x11400
	s_add_u32 s2, s14, 0xa000
	s_addc_u32 s3, s15, 0
	v_xor_b32_e32 v135, 0xa0, v134
	global_load_lds_dwordx4 v135, s[2:3]
	s_add_i32 m0, s7, 0x11800
	s_add_u32 s2, s14, 0xc000
	s_addc_u32 s3, s15, 0
	v_xor_b32_e32 v135, 0xc0, v134
	global_load_lds_dwordx4 v135, s[2:3]
	s_add_i32 m0, s7, 0x11c00
	s_add_u32 s2, s14, 0xe000
	s_addc_u32 s3, s15, 0
	v_xor_b32_e32 v135, 0xe0, v134
	global_load_lds_dwordx4 v135, s[2:3]
	s_waitcnt vmcnt(0)
	s_barrier
	v_lshl_add_u32 v138, s4, 8, v235
	v_lshl_or_b32 v136, s6, 8, v237
	v_ashrrev_i32_e32 v139, 31, v138
	v_ashrrev_i32_e32 v137, 31, v136
	v_lshlrev_b64 v[140:141], 11, v[138:139]
	v_lshl_add_u64 v[142:143], v[140:141], 0, v[136:137]
	v_lshl_add_u64 v[140:141], v[138:139], 2, s[54:55]
	v_lshlrev_b64 v[142:143], 1, v[142:143]
	v_lshl_add_u64 v[144:145], s[46:47], 0, v[142:143]
	global_load_dword v250, v[140:141], off
	ds_read_b64 v[242:243], v130 offset:0
	v_lshl_add_u64 v[144:145], s[52:53], 0, v[142:143]
	v_or_b32_e32 v146, 32, v142
	v_mov_b32_e32 v147, v143
	v_or_b32_e32 v150, 0x100, v142
	v_mov_b32_e32 v151, v143
	v_lshl_add_u64 v[148:149], s[46:47], 0, v[146:147]
	v_lshl_add_u64 v[146:147], s[52:53], 0, v[146:147]
	v_lshl_add_u64 v[152:153], s[46:47], 0, v[150:151]
	ds_read_b64 v[244:245], v132 offset:0
	ds_read_b64 v[246:247], v131 offset:0
	ds_read_b64 v[248:249], v133 offset:0
	ds_read_b64 v[212:213], v130 offset:256
	v_or_b32_e32 v204, 16, v138
	v_ashrrev_i32_e32 v205, 31, v204
	v_lshlrev_b64 v[148:149], 11, v[204:205]
	v_lshl_add_u64 v[148:149], v[148:149], 0, v[136:137]
	v_lshl_add_u64 v[144:145], s[52:53], 0, v[150:151]
	v_or_b32_e32 v142, 0x120, v142
	v_lshlrev_b64 v[148:149], 1, v[148:149]
	v_lshl_add_u64 v[146:147], s[46:47], 0, v[142:143]
	v_lshl_add_u64 v[142:143], s[52:53], 0, v[142:143]
	v_lshl_add_u64 v[150:151], s[46:47], 0, v[148:149]
	ds_read_b64 v[210:211], v132 offset:256
	ds_read_b64 v[208:209], v131 offset:256
	ds_read_b64 v[206:207], v133 offset:256
	ds_read_b64 v[202:203], v130 offset:8192
	v_or_b32_e32 v144, 32, v148
	v_mov_b32_e32 v145, v149
	v_or_b32_e32 v176, 32, v138
	v_lshl_add_u64 v[142:143], s[52:53], 0, v[148:149]
	v_lshl_add_u64 v[146:147], s[46:47], 0, v[144:145]
	v_lshl_add_u64 v[144:145], s[52:53], 0, v[144:145]
	v_or_b32_e32 v150, 0x100, v148
	v_mov_b32_e32 v151, v149
	v_or_b32_e32 v148, 0x120, v148
	v_ashrrev_i32_e32 v177, 31, v176
	v_lshl_add_u64 v[152:153], s[46:47], 0, v[150:151]
	ds_read_b64 v[200:201], v132 offset:8192
	ds_read_b64 v[198:199], v131 offset:8192
	ds_read_b64 v[196:197], v133 offset:8192
	ds_read_b64 v[194:195], v130 offset:8448
	v_lshl_add_u64 v[144:145], s[46:47], 0, v[148:149]
	v_lshl_add_u64 v[146:147], s[52:53], 0, v[148:149]
	v_lshlrev_b64 v[148:149], 11, v[176:177]
	v_lshl_add_u64 v[148:149], v[148:149], 0, v[136:137]
	v_lshl_add_u64 v[142:143], s[52:53], 0, v[150:151]
	v_lshlrev_b64 v[148:149], 1, v[148:149]
;     __device__ __forceinline__ void operator()(const f32x4 (&acc)[2][2][4][2], const Unit& u, int wr, int wc, int fr, int fq) const {
;     ...
;             for (int m = 0; m < 4; ++m) { const int row = row0 + ai * HALF + m * 16; const size_t ro = (size_t)row * 2048 + col0;
;                 scv[m] = GATE ? rss_in[row] : 0.f;
; #pragma unroll
;                 for (int bj = 0; bj < 2; ++bj)
; #pragma unroll
;                     for (int n = 0; n < 2; ++n) { const size_t p = ro + bj * HALF + n * 16; hw[m][bj][n] = *(const u32x2e*)(Hin + p); if (GATE) pw[m][bj][n] = *(const u32x2e*)(PP + p); else pw[m][bj][n] = (u32x2e){0u, 0u}; } }
; #pragma unroll
;             for (int m = 0; m < 4; ++m) { const int row = row0 + ai * HALF + m * 16; const size_t ro = (size_t)row * 2048 + col0;
;                 float sc = 1.f; if (GATE) sc = rsqrtf(scv[m] * (1.f / 2048.f) + 1e-6f);
;                 float s = 0.f;
; #pragma unroll
;                 for (int bj = 0; bj < 2; ++bj)
; #pragma unroll
;                     for (int n = 0; n < 2; ++n) { const size_t p = ro + bj * HALF + n * 16; const u32x2e hh = hw[m][bj][n], pp = pw[m][bj][n]; const f32x4 a = acc[ai][bj][m][n];
;                         f32x4 h; h[0] = __uint_as_float(hh.x << 16); h[1] = __uint_as_float(hh.x & 0xffff0000u); h[2] = __uint_as_float(hh.y << 16); h[3] = __uint_as_float(hh.y & 0xffff0000u);
;                         if (GATE) {
;                             h[0] += __builtin_amdgcn_rcpf(1.f + __expf(-sc * a[0])) * __uint_as_float(pp.x << 16); h[1] += __builtin_amdgcn_rcpf(1.f + __expf(-sc * a[1])) * __uint_as_float(pp.x & 0xffff0000u);
;                             h[2] += __builtin_amdgcn_rcpf(1.f + __expf(-sc * a[2])) * __uint_as_float(pp.y << 16); h[3] += __builtin_amdgcn_rcpf(1.f + __expf(-sc * a[3])) * __uint_as_float(pp.y & 0xffff0000u); }
	v_lshl_add_u64 v[150:151], s[46:47], 0, v[148:149]
	ds_read_b64 v[192:193], v132 offset:8448
	ds_read_b64 v[180:181], v131 offset:8448
	ds_read_b64 v[178:179], v133 offset:8448
	ds_read_b64 v[174:175], v130 offset:16384
	v_or_b32_e32 v144, 32, v148
	v_mov_b32_e32 v145, v149
	v_or_b32_e32 v158, 48, v138
	v_lshl_add_u64 v[142:143], s[52:53], 0, v[148:149]
	v_lshl_add_u64 v[146:147], s[46:47], 0, v[144:145]
	v_lshl_add_u64 v[144:145], s[52:53], 0, v[144:145]
	v_or_b32_e32 v150, 0x100, v148
	v_mov_b32_e32 v151, v149
	v_or_b32_e32 v148, 0x120, v148
	v_ashrrev_i32_e32 v159, 31, v158
	v_lshl_add_u64 v[152:153], s[46:47], 0, v[150:151]
	ds_read_b64 v[172:173], v132 offset:16384
	ds_read_b64 v[170:171], v131 offset:16384
	ds_read_b64 v[168:169], v133 offset:16384
	ds_read_b64 v[166:167], v130 offset:16640
	v_lshl_add_u64 v[144:145], s[46:47], 0, v[148:149]
	v_lshl_add_u64 v[146:147], s[52:53], 0, v[148:149]
	v_lshlrev_b64 v[148:149], 11, v[158:159]
	v_lshl_add_u64 v[148:149], v[148:149], 0, v[136:137]
	v_lshl_add_u64 v[142:143], s[52:53], 0, v[150:151]
	v_lshlrev_b64 v[226:227], 1, v[148:149]
	global_load_dword v241, v[140:141], off offset:64
	global_load_dword v240, v[140:141], off offset:128
	global_load_dword v239, v[140:141], off offset:192
	v_lshl_add_u64 v[148:149], s[46:47], 0, v[226:227]
	ds_read_b64 v[164:165], v132 offset:16640
	ds_read_b64 v[162:163], v131 offset:16640
	ds_read_b64 v[160:161], v133 offset:16640
	ds_read_b64 v[156:157], v130 offset:24576
	v_or_b32_e32 v144, 32, v226
	v_mov_b32_e32 v145, v227
	v_or_b32_e32 v222, 0x100, v226
	v_mov_b32_e32 v223, v227
	v_lshl_add_u64 v[142:143], s[52:53], 0, v[226:227]
	v_lshl_add_u64 v[146:147], s[46:47], 0, v[144:145]
	v_lshl_add_u64 v[148:149], s[46:47], 0, v[222:223]
	v_lshl_add_u64 v[144:145], s[52:53], 0, v[144:145]
	ds_read_b64 v[154:155], v132 offset:24576
	ds_read_b64 v[152:153], v131 offset:24576
	ds_read_b64 v[150:151], v133 offset:24576
	s_nop 0
	ds_read_b64 v[148:149], v130 offset:24832
	v_or_b32_e32 v226, 0x120, v226
	v_lshl_add_u64 v[142:143], s[52:53], 0, v[222:223]
	v_lshl_add_u64 v[144:145], s[46:47], 0, v[226:227]
	v_lshl_add_u64 v[222:223], s[52:53], 0, v[226:227]
	s_waitcnt vmcnt(0) lgkmcnt(0)
	v_fmamk_f32 v146, v250, 0x3a000000, v214
	v_mul_f32_e32 v147, 0x4b800000, v146
	v_cmp_gt_f32_e32 vcc, s65, v146
	v_lshlrev_b32_e32 v227, 16, v242
	v_and_b32_e32 v242, 0xffff0000, v242
	v_cndmask_b32_e32 v146, v146, v147, vcc
	v_rsq_f32_e32 v226, v146
	ds_read_b64 v[146:147], v132 offset:24832
	s_nop 0
	ds_read_b64 v[144:145], v131 offset:24832
	s_nop 0
	ds_read_b64 v[142:143], v133 offset:24832
	s_waitcnt vmcnt(0) lgkmcnt(0)
	s_barrier
	s_add_i32 m0, s7, 0x0
	s_add_u32 s2, s10, 0x80000
	s_addc_u32 s3, s11, 0
	v_xor_b32_e32 v135, 0x0, v134
	global_load_lds_dwordx4 v135, s[2:3]
	s_add_i32 m0, s7, 0x400
	s_add_u32 s2, s10, 0x82000
	s_addc_u32 s3, s11, 0
	v_xor_b32_e32 v135, 0x20, v134
	global_load_lds_dwordx4 v135, s[2:3]
	s_add_i32 m0, s7, 0x800
	s_add_u32 s2, s10, 0x84000
	s_addc_u32 s3, s11, 0
	v_xor_b32_e32 v135, 0x40, v134
	global_load_lds_dwordx4 v135, s[2:3]
	s_add_i32 m0, s7, 0xc00
	s_add_u32 s2, s10, 0x86000
	s_addc_u32 s3, s11, 0
	v_xor_b32_e32 v135, 0x60, v134
	global_load_lds_dwordx4 v135, s[2:3]
	s_add_i32 m0, s7, 0x1000
	s_add_u32 s2, s10, 0x88000
	s_addc_u32 s3, s11, 0
	v_xor_b32_e32 v135, 0x80, v134
	global_load_lds_dwordx4 v135, s[2:3]
	s_add_i32 m0, s7, 0x1400
	s_add_u32 s2, s10, 0x8a000
	s_addc_u32 s3, s11, 0
	v_xor_b32_e32 v135, 0xa0, v134
	global_load_lds_dwordx4 v135, s[2:3]
	s_add_i32 m0, s7, 0x1800
	s_add_u32 s2, s10, 0x8c000
	s_addc_u32 s3, s11, 0
	v_xor_b32_e32 v135, 0xc0, v134
	global_load_lds_dwordx4 v135, s[2:3]
	s_add_i32 m0, s7, 0x1c00
	s_add_u32 s2, s10, 0x8e000
	s_addc_u32 s3, s11, 0
	v_xor_b32_e32 v135, 0xe0, v134
	global_load_lds_dwordx4 v135, s[2:3]
	s_add_i32 m0, s7, 0x10000
	s_add_u32 s2, s14, 0x80000
	s_addc_u32 s3, s15, 0
	v_xor_b32_e32 v135, 0x0, v134
	global_load_lds_dwordx4 v135, s[2:3]
	s_add_i32 m0, s7, 0x10400
	s_add_u32 s2, s14, 0x82000
	s_addc_u32 s3, s15, 0
	v_xor_b32_e32 v135, 0x20, v134
	global_load_lds_dwordx4 v135, s[2:3]
	s_add_i32 m0, s7, 0x10800
	s_add_u32 s2, s14, 0x84000
	s_addc_u32 s3, s15, 0
	v_xor_b32_e32 v135, 0x40, v134
	global_load_lds_dwordx4 v135, s[2:3]
	s_add_i32 m0, s7, 0x10c00
	s_add_u32 s2, s14, 0x86000
	s_addc_u32 s3, s15, 0
	v_xor_b32_e32 v135, 0x60, v134
	global_load_lds_dwordx4 v135, s[2:3]
	s_add_i32 m0, s7, 0x11000
	s_add_u32 s2, s14, 0x88000
	s_addc_u32 s3, s15, 0
	v_xor_b32_e32 v135, 0x80, v134
	global_load_lds_dwordx4 v135, s[2:3]
	s_add_i32 m0, s7, 0x11400
	s_add_u32 s2, s14, 0x8a000
	s_addc_u32 s3, s15, 0
	v_xor_b32_e32 v135, 0xa0, v134
	global_load_lds_dwordx4 v135, s[2:3]
	s_add_i32 m0, s7, 0x11800
	s_add_u32 s2, s14, 0x8c000
	s_addc_u32 s3, s15, 0
	v_xor_b32_e32 v135, 0xc0, v134
	global_load_lds_dwordx4 v135, s[2:3]
	s_add_i32 m0, s7, 0x11c00
	s_add_u32 s2, s14, 0x8e000
	s_addc_u32 s3, s15, 0
	v_xor_b32_e32 v135, 0xe0, v134
	global_load_lds_dwordx4 v135, s[2:3]
	v_lshlrev_b32_e32 v225, 16, v244
	v_lshlrev_b32_e32 v250, 16, v243
	v_mul_f32_e32 v222, 0x45800000, v226
	v_cndmask_b32_e32 v226, v226, v222, vcc
	v_mul_f32_e64 v126, v126, -v226
	v_mul_f32_e32 v126, 0x3fb8aa3b, v126
	v_exp_f32_e32 v126, v126
	v_mul_f32_e64 v127, v127, -v226
	v_mul_f32_e32 v127, 0x3fb8aa3b, v127
	v_exp_f32_e32 v127, v127
	v_add_f32_e32 v126, 1.0, v126
	v_rcp_f32_e32 v126, v126
	v_mul_f32_e64 v128, v128, -v226
	v_mul_f32_e32 v128, 0x3fb8aa3b, v128
	v_mul_f32_e64 v129, v129, -v226
	v_fmac_f32_e32 v227, v126, v225
	v_add_f32_e32 v126, 1.0, v127
	v_rcp_f32_e32 v126, v126
	v_exp_f32_e32 v128, v128
	v_mul_f32_e32 v129, 0x3fb8aa3b, v129
; __device__ __forceinline__ unsigned cvt_pk_bf16(float lo, float hi) { unsigned r; asm volatile("v_cvt_pk_bf16_f32 %0, %1, %2" : "=v"(r) : "v"(lo), "v"(hi)); return r; }
;     __device__ __forceinline__ void operator()(const f32x4 (&acc)[2][2][4][2], const Unit& u, int wr, int wc, int fr, int fq) const {
;     ...
;             for (int m = 0; m < 4; ++m) { const int row = row0 + ai * HALF + m * 16; const size_t ro = (size_t)row * 2048 + col0;
;                 float sc = 1.f; if (GATE) sc = rsqrtf(scv[m] * (1.f / 2048.f) + 1e-6f);
;                 float s = 0.f;
; #pragma unroll
;                 for (int bj = 0; bj < 2; ++bj)
; #pragma unroll
;                     for (int n = 0; n < 2; ++n) { const size_t p = ro + bj * HALF + n * 16; const u32x2e hh = hw[m][bj][n], pp = pw[m][bj][n]; const f32x4 a = acc[ai][bj][m][n];
;                         f32x4 h; h[0] = __uint_as_float(hh.x << 16); h[1] = __uint_as_float(hh.x & 0xffff0000u); h[2] = __uint_as_float(hh.y << 16); h[3] = __uint_as_float(hh.y & 0xffff0000u);
;                         if (GATE) {
;                             h[0] += __builtin_amdgcn_rcpf(1.f + __expf(-sc * a[0])) * __uint_as_float(pp.x << 16); h[1] += __builtin_amdgcn_rcpf(1.f + __expf(-sc * a[1])) * __uint_as_float(pp.x & 0xffff0000u);
;                             h[2] += __builtin_amdgcn_rcpf(1.f + __expf(-sc * a[2])) * __uint_as_float(pp.y << 16); h[3] += __builtin_amdgcn_rcpf(1.f + __expf(-sc * a[3])) * __uint_as_float(pp.y & 0xffff0000u); }
;                         else h = h + a;
;                         s += (h[0] * h[0] + h[1] * h[1]) + (h[2] * h[2] + h[3] * h[3]);
;                         u32x2e o; o.x = cvt_pk_bf16(h[0], h[1]); o.y = cvt_pk_bf16(h[2], h[3]); *(u32x2e*)(Hout + p) = o; }
;                 s += __shfl_xor(s, 16); s += __shfl_xor(s, 32);
;                 if (fq == 0) atomicAdd(rss_out + row, s); }
	v_exp_f32_e32 v129, v129
	v_and_b32_e32 v127, 0xffff0000, v244
	v_fmac_f32_e32 v242, v126, v127
	v_add_f32_e32 v126, 1.0, v128
	v_mul_f32_e64 v122, v122, -v226
	v_rcp_f32_e32 v126, v126
	v_add_f32_e32 v127, 1.0, v129
	v_mul_f32_e32 v122, 0x3fb8aa3b, v122
	v_rcp_f32_e32 v127, v127
	v_exp_f32_e32 v122, v122
	v_lshlrev_b32_e32 v128, 16, v245
	v_and_b32_e32 v243, 0xffff0000, v243
	v_fmac_f32_e32 v250, v126, v128
	v_and_b32_e32 v126, 0xffff0000, v245
	v_mul_f32_e64 v123, v123, -v226
	v_fmac_f32_e32 v243, v127, v126
	v_add_f32_e32 v122, 1.0, v122
	v_mul_f32_e32 v123, 0x3fb8aa3b, v123
	v_lshlrev_b64 v[222:223], 12, v[138:139]
	v_mul_f32_e32 v126, v242, v242
	v_mul_f32_e32 v127, v243, v243
	v_rcp_f32_e32 v122, v122
	v_exp_f32_e32 v123, v123
	v_fmac_f32_e32 v126, v227, v227
	v_fmac_f32_e32 v127, v250, v250
	v_lshl_add_u64 v[128:129], s[48:49], 0, v[222:223]
	v_add_f32_e32 v225, v126, v127
	v_cvt_pk_bf16_f32 v126, v227, v242
	v_lshl_add_u64 v[128:129], v[136:137], 1, v[128:129]
	v_cvt_pk_bf16_f32 v127, v250, v243
	v_bfe_u32 v250, v237, 2, 1
	v_mul_u32_u24_e32 v250, 24, v250
	v_add_u32_e32 v128, v250, v128
	v_mov_b32_e32 v242, v126
	v_mov_b32_e32 v243, v127
	v_lshlrev_b32_e32 v126, 16, v246
	v_lshlrev_b32_e32 v227, 16, v248
	v_mul_f32_e64 v124, v124, -v226
	v_fmac_f32_e32 v126, v122, v227
	v_add_f32_e32 v122, 1.0, v123
	v_mul_f32_e32 v124, 0x3fb8aa3b, v124
	v_mul_f32_e64 v125, v125, -v226
	v_rcp_f32_e32 v122, v122
	v_exp_f32_e32 v124, v124
	v_mul_f32_e32 v125, 0x3fb8aa3b, v125
	v_exp_f32_e32 v125, v125
	v_and_b32_e32 v127, 0xffff0000, v246
	v_and_b32_e32 v123, 0xffff0000, v248
	v_fmac_f32_e32 v127, v122, v123
	v_add_f32_e32 v122, 1.0, v124
	v_mul_f32_e64 v118, v118, -v226
	v_rcp_f32_e32 v122, v122
	v_add_f32_e32 v123, 1.0, v125
	v_mul_f32_e32 v118, 0x3fb8aa3b, v118
	v_rcp_f32_e32 v123, v123
	v_exp_f32_e32 v118, v118
	v_lshlrev_b32_e32 v222, 16, v247
	v_lshlrev_b32_e32 v124, 16, v249
	v_and_b32_e32 v223, 0xffff0000, v247
	v_fmac_f32_e32 v222, v122, v124
	v_and_b32_e32 v122, 0xffff0000, v249
	v_mul_f32_e64 v119, v119, -v226
	v_fmac_f32_e32 v223, v123, v122
	v_add_f32_e32 v118, 1.0, v118
	v_mul_f32_e32 v119, 0x3fb8aa3b, v119
	v_mul_f32_e32 v122, v127, v127
	v_mul_f32_e32 v123, v223, v223
	v_rcp_f32_e32 v118, v118
	v_exp_f32_e32 v119, v119
	v_fmac_f32_e32 v122, v126, v126
	v_fmac_f32_e32 v123, v222, v222
	v_add_f32_e32 v122, v122, v123
	v_add_f32_e32 v124, v225, v122
	v_cvt_pk_bf16_f32 v122, v126, v127
	v_lshlrev_b32_e32 v125, 16, v212
	v_and_b32_e32 v126, 0xffff0000, v212
	v_lshlrev_b32_e32 v127, 16, v213
	v_and_b32_e32 v212, 0xffff0000, v213
	v_lshlrev_b32_e32 v213, 16, v210
	v_mul_f32_e64 v120, v120, -v226
	v_fmac_f32_e32 v125, v118, v213
	v_add_f32_e32 v118, 1.0, v119
	v_mul_f32_e32 v120, 0x3fb8aa3b, v120
	v_mul_f32_e64 v121, v121, -v226
	v_rcp_f32_e32 v118, v118
	v_exp_f32_e32 v120, v120
	v_mul_f32_e32 v121, 0x3fb8aa3b, v121
	v_exp_f32_e32 v121, v121
	v_and_b32_e32 v119, 0xffff0000, v210
	v_mul_f32_e64 v114, v114, -v226
	v_fmac_f32_e32 v126, v118, v119
	v_add_f32_e32 v118, 1.0, v120
	v_mul_f32_e32 v114, 0x3fb8aa3b, v114
	v_rcp_f32_e32 v118, v118
	v_add_f32_e32 v119, 1.0, v121
	v_exp_f32_e32 v114, v114
	v_rcp_f32_e32 v119, v119
	v_lshlrev_b32_e32 v120, 16, v211
	v_mul_f32_e64 v115, v115, -v226
	v_fmac_f32_e32 v127, v118, v120
	v_and_b32_e32 v118, 0xffff0000, v211
	v_add_f32_e32 v114, 1.0, v114
	v_mul_f32_e32 v115, 0x3fb8aa3b, v115
	v_fmac_f32_e32 v212, v119, v118
	v_rcp_f32_e32 v114, v114
	v_exp_f32_e32 v115, v115
	v_mul_f32_e32 v118, v126, v126
	v_mul_f32_e32 v119, v212, v212
	v_fmac_f32_e32 v118, v125, v125
	v_fmac_f32_e32 v119, v127, v127
	v_add_f32_e32 v118, v118, v119
	v_lshlrev_b32_e32 v119, 16, v208
	v_and_b32_e32 v120, 0xffff0000, v208
	v_lshlrev_b32_e32 v208, 16, v206
	v_mul_f32_e64 v116, v116, -v226
	v_fmac_f32_e32 v119, v114, v208
	v_add_f32_e32 v114, 1.0, v115
	v_mul_f32_e32 v116, 0x3fb8aa3b, v116
	v_mul_f32_e64 v117, v117, -v226
	v_rcp_f32_e32 v114, v114
	v_exp_f32_e32 v116, v116
	v_mul_f32_e32 v117, 0x3fb8aa3b, v117
	v_exp_f32_e32 v117, v117
	v_and_b32_e32 v115, 0xffff0000, v206
	v_fmac_f32_e32 v120, v114, v115
	v_add_f32_e32 v114, 1.0, v116
	v_rcp_f32_e32 v114, v114
	v_add_f32_e32 v115, 1.0, v117
	v_rcp_f32_e32 v115, v115
	v_lshlrev_b32_e32 v121, 16, v209
	v_lshlrev_b32_e32 v116, 16, v207
	v_add_f32_e32 v118, v118, v124
	v_and_b32_e32 v124, 0xffff0000, v209
	v_fmac_f32_e32 v121, v114, v116
	v_and_b32_e32 v114, 0xffff0000, v207
	v_fmac_f32_e32 v124, v115, v114
	v_mul_f32_e32 v114, v120, v120
	v_mul_f32_e32 v115, v124, v124
	v_fmac_f32_e32 v114, v119, v119
	v_fmac_f32_e32 v115, v121, v121
	v_add_f32_e32 v114, v114, v115
	v_and_b32_e32 v115, 64, v216
	v_add_f32_e32 v116, v114, v118
	v_xor_b32_e32 v114, 16, v216
	v_add_u32_e32 v117, 64, v115
	v_cmp_lt_i32_e32 vcc, v114, v117
	v_cvt_pk_bf16_f32 v123, v222, v223
	v_mov_b32_e32 v244, v122
	v_mov_b32_e32 v245, v123
	s_nop 1
	v_permlane16_swap_b32 v242, v244
	v_permlane16_swap_b32 v243, v245
	global_store_dwordx4 v[128:129], v[242:245], off
	s_nop 0
	v_cndmask_b32_e32 v114, v216, v114, vcc
	v_lshlrev_b32_e32 v206, 2, v114
	ds_bpermute_b32 v118, v206, v116
	v_cvt_pk_bf16_f32 v114, v125, v126
	v_cvt_pk_bf16_f32 v115, v127, v212
	v_mov_b32_e32 v242, v114
	v_mov_b32_e32 v243, v115
	v_xor_b32_e32 v114, 32, v216
	v_cmp_lt_i32_e32 vcc, v114, v117
	s_waitcnt lgkmcnt(0)
	v_add_f32_e32 v116, v116, v118
	v_cndmask_b32_e32 v114, v216, v114, vcc
	v_lshlrev_b32_e32 v207, 2, v114
	ds_bpermute_b32 v117, v207, v116
	v_cvt_pk_bf16_f32 v114, v119, v120
	v_cvt_pk_bf16_f32 v115, v121, v124
	v_mov_b32_e32 v244, v114
	v_mov_b32_e32 v245, v115
	s_nop 1
	v_permlane16_swap_b32 v242, v244
	v_permlane16_swap_b32 v243, v245
	global_store_dwordx4 v[128:129], v[242:245], off offset:256
	v_lshl_add_u64 v[114:115], v[138:139], 2, s[50:51]
	s_and_saveexec_b64 s[0:1], s[42:43]
	s_cbranch_execz .LBB0_47
	s_waitcnt lgkmcnt(0)
	v_add_f32_e32 v116, v116, v117
	global_atomic_add_f32 v[114:115], v116, off
; __device__ __forceinline__ unsigned cvt_pk_bf16(float lo, float hi) { unsigned r; asm volatile("v_cvt_pk_bf16_f32 %0, %1, %2" : "=v"(r) : "v"(lo), "v"(hi)); return r; }
;     __device__ __forceinline__ void operator()(const f32x4 (&acc)[2][2][4][2], const Unit& u, int wr, int wc, int fr, int fq) const {
;     ...
;             for (int m = 0; m < 4; ++m) { const int row = row0 + ai * HALF + m * 16; const size_t ro = (size_t)row * 2048 + col0;
;                 float sc = 1.f; if (GATE) sc = rsqrtf(scv[m] * (1.f / 2048.f) + 1e-6f);
;                 float s = 0.f;
; #pragma unroll
;                 for (int bj = 0; bj < 2; ++bj)
; #pragma unroll
;                     for (int n = 0; n < 2; ++n) { const size_t p = ro + bj * HALF + n * 16; const u32x2e hh = hw[m][bj][n], pp = pw[m][bj][n]; const f32x4 a = acc[ai][bj][m][n];
;                         f32x4 h; h[0] = __uint_as_float(hh.x << 16); h[1] = __uint_as_float(hh.x & 0xffff0000u); h[2] = __uint_as_float(hh.y << 16); h[3] = __uint_as_float(hh.y & 0xffff0000u);
;                         if (GATE) {
;                             h[0] += __builtin_amdgcn_rcpf(1.f + __expf(-sc * a[0])) * __uint_as_float(pp.x << 16); h[1] += __builtin_amdgcn_rcpf(1.f + __expf(-sc * a[1])) * __uint_as_float(pp.x & 0xffff0000u);
;                             h[2] += __builtin_amdgcn_rcpf(1.f + __expf(-sc * a[2])) * __uint_as_float(pp.y << 16); h[3] += __builtin_amdgcn_rcpf(1.f + __expf(-sc * a[3])) * __uint_as_float(pp.y & 0xffff0000u); }
;                         else h = h + a;
;                         s += (h[0] * h[0] + h[1] * h[1]) + (h[2] * h[2] + h[3] * h[3]);
;                         u32x2e o; o.x = cvt_pk_bf16(h[0], h[1]); o.y = cvt_pk_bf16(h[2], h[3]); *(u32x2e*)(Hout + p) = o; }
;                 s += __shfl_xor(s, 16); s += __shfl_xor(s, 32);
;                 if (fq == 0) atomicAdd(rss_out + row, s); }
.LBB0_47:
	s_or_b64 exec, exec, s[0:1]
	v_fmamk_f32 v116, v241, 0x3a000000, v214
	s_waitcnt lgkmcnt(0)
	v_mul_f32_e32 v117, 0x4b800000, v116
	v_cmp_gt_f32_e32 vcc, s65, v116
	v_lshlrev_b32_e32 v119, 16, v202
	v_lshlrev_b32_e32 v123, 16, v200
	v_cndmask_b32_e32 v116, v116, v117, vcc
	v_rsq_f32_e32 v118, v116
	v_lshlrev_b32_e32 v121, 16, v203
	v_and_b32_e32 v122, 0xffff0000, v203
	v_lshlrev_b64 v[116:117], 12, v[204:205]
	v_mul_f32_e32 v120, 0x45800000, v118
	v_cndmask_b32_e32 v118, v118, v120, vcc
	v_mul_f32_e64 v110, v110, -v118
	v_mul_f32_e32 v110, 0x3fb8aa3b, v110
	v_exp_f32_e32 v110, v110
	v_mul_f32_e64 v111, v111, -v118
	v_mul_f32_e32 v111, 0x3fb8aa3b, v111
	v_exp_f32_e32 v111, v111
	v_add_f32_e32 v110, 1.0, v110
	v_rcp_f32_e32 v110, v110
	v_mul_f32_e64 v112, v112, -v118
	v_mul_f32_e32 v112, 0x3fb8aa3b, v112
	v_mul_f32_e64 v113, v113, -v118
	v_fmac_f32_e32 v119, v110, v123
	v_add_f32_e32 v110, 1.0, v111
	v_rcp_f32_e32 v110, v110
	v_exp_f32_e32 v112, v112
	v_mul_f32_e32 v113, 0x3fb8aa3b, v113
	v_exp_f32_e32 v113, v113
	v_and_b32_e32 v120, 0xffff0000, v202
	v_and_b32_e32 v111, 0xffff0000, v200
	v_fmac_f32_e32 v120, v110, v111
	v_add_f32_e32 v110, 1.0, v112
	v_mul_f32_e64 v106, v106, -v118
	v_rcp_f32_e32 v110, v110
	v_add_f32_e32 v111, 1.0, v113
	v_mul_f32_e32 v106, 0x3fb8aa3b, v106
	v_rcp_f32_e32 v111, v111
	v_exp_f32_e32 v106, v106
	v_lshlrev_b32_e32 v112, 16, v201
	v_fmac_f32_e32 v121, v110, v112
	v_and_b32_e32 v110, 0xffff0000, v201
	v_mul_f32_e64 v107, v107, -v118
	v_fmac_f32_e32 v122, v111, v110
	v_add_f32_e32 v106, 1.0, v106
	v_mul_f32_e32 v107, 0x3fb8aa3b, v107
	v_mul_f32_e32 v110, v120, v120
	v_mul_f32_e32 v111, v122, v122
	v_rcp_f32_e32 v106, v106
	v_exp_f32_e32 v107, v107
	v_fmac_f32_e32 v110, v119, v119
	v_fmac_f32_e32 v111, v121, v121
	v_lshl_add_u64 v[112:113], s[48:49], 0, v[116:117]
	v_add_f32_e32 v123, v110, v111
	v_cvt_pk_bf16_f32 v110, v119, v120
	v_lshl_add_u64 v[112:113], v[136:137], 1, v[112:113]
	v_cvt_pk_bf16_f32 v111, v121, v122
	v_add_u32_e32 v112, v250, v112
	v_mov_b32_e32 v242, v110
	v_mov_b32_e32 v243, v111
	v_lshlrev_b32_e32 v110, 16, v198
	v_lshlrev_b32_e32 v119, 16, v196
	v_mul_f32_e64 v108, v108, -v118
	v_fmac_f32_e32 v110, v106, v119
	v_add_f32_e32 v106, 1.0, v107
	v_mul_f32_e32 v108, 0x3fb8aa3b, v108
	v_mul_f32_e64 v102, v102, -v118
	v_rcp_f32_e32 v106, v106
	v_exp_f32_e32 v108, v108
	v_mul_f32_e32 v102, 0x3fb8aa3b, v102
	v_exp_f32_e32 v102, v102
	v_and_b32_e32 v111, 0xffff0000, v198
	v_and_b32_e32 v107, 0xffff0000, v196
	v_mul_f32_e64 v109, v109, -v118
	v_fmac_f32_e32 v111, v106, v107
	v_add_f32_e32 v106, 1.0, v108
	v_mul_f32_e64 v103, v103, -v118
	v_mul_f32_e32 v109, 0x3fb8aa3b, v109
	v_rcp_f32_e32 v106, v106
	v_add_f32_e32 v102, 1.0, v102
	v_mul_f32_e32 v103, 0x3fb8aa3b, v103
	v_exp_f32_e32 v109, v109
	v_rcp_f32_e32 v102, v102
	v_exp_f32_e32 v103, v103
	v_lshlrev_b32_e32 v116, 16, v199
	v_lshlrev_b32_e32 v108, 16, v197
	v_fmac_f32_e32 v116, v106, v108
	v_lshlrev_b32_e32 v108, 16, v194
	v_lshlrev_b32_e32 v119, 16, v192
	v_mul_f32_e64 v104, v104, -v118
	v_add_f32_e32 v107, 1.0, v109
	v_fmac_f32_e32 v108, v102, v119
	v_add_f32_e32 v102, 1.0, v103
	v_mul_f32_e32 v104, 0x3fb8aa3b, v104
	v_mul_f32_e64 v105, v105, -v118
	v_rcp_f32_e32 v107, v107
	v_rcp_f32_e32 v102, v102
	v_exp_f32_e32 v104, v104
	v_mul_f32_e32 v105, 0x3fb8aa3b, v105
	v_exp_f32_e32 v105, v105
	v_and_b32_e32 v117, 0xffff0000, v199
	v_and_b32_e32 v106, 0xffff0000, v197
	v_and_b32_e32 v109, 0xffff0000, v194
	v_and_b32_e32 v103, 0xffff0000, v192
	v_fmac_f32_e32 v117, v107, v106
	v_fmac_f32_e32 v109, v102, v103
	v_add_f32_e32 v102, 1.0, v104
	v_mul_f32_e64 v98, v98, -v118
	v_mul_f32_e32 v106, v111, v111
	v_mul_f32_e32 v107, v117, v117
	v_rcp_f32_e32 v102, v102
	v_add_f32_e32 v103, 1.0, v105
	v_mul_f32_e32 v98, 0x3fb8aa3b, v98
	v_fmac_f32_e32 v106, v110, v110
	v_fmac_f32_e32 v107, v116, v116
	v_rcp_f32_e32 v103, v103
	v_exp_f32_e32 v98, v98
	v_add_f32_e32 v106, v106, v107
	v_add_f32_e32 v107, v123, v106
	v_cvt_pk_bf16_f32 v106, v110, v111
	v_lshlrev_b32_e32 v110, 16, v195
	v_lshlrev_b32_e32 v104, 16, v193
	v_and_b32_e32 v111, 0xffff0000, v195
	v_fmac_f32_e32 v110, v102, v104
	v_and_b32_e32 v102, 0xffff0000, v193
	v_mul_f32_e64 v99, v99, -v118
	v_fmac_f32_e32 v111, v103, v102
	v_add_f32_e32 v98, 1.0, v98
	v_mul_f32_e32 v99, 0x3fb8aa3b, v99
	v_mul_f32_e32 v102, v109, v109
	v_mul_f32_e32 v103, v111, v111
	v_rcp_f32_e32 v98, v98
	v_exp_f32_e32 v99, v99
	v_fmac_f32_e32 v102, v108, v108
	v_fmac_f32_e32 v103, v110, v110
	v_add_f32_e32 v102, v102, v103
	v_add_f32_e32 v102, v102, v107
	v_lshlrev_b32_e32 v103, 16, v180
	v_lshlrev_b32_e32 v107, 16, v178
	v_mul_f32_e64 v100, v100, -v118
	v_fmac_f32_e32 v103, v98, v107
	v_add_f32_e32 v98, 1.0, v99
	v_mul_f32_e32 v100, 0x3fb8aa3b, v100
	v_mul_f32_e64 v101, v101, -v118
	v_rcp_f32_e32 v98, v98
	v_exp_f32_e32 v100, v100
	v_mul_f32_e32 v101, 0x3fb8aa3b, v101
	v_exp_f32_e32 v101, v101
	v_and_b32_e32 v104, 0xffff0000, v180
	v_and_b32_e32 v99, 0xffff0000, v178
	v_fmac_f32_e32 v104, v98, v99
	v_add_f32_e32 v98, 1.0, v100
	v_rcp_f32_e32 v98, v98
	v_add_f32_e32 v99, 1.0, v101
	v_rcp_f32_e32 v99, v99
	v_lshlrev_b32_e32 v105, 16, v181
	v_lshlrev_b32_e32 v100, 16, v179
	v_and_b32_e32 v119, 0xffff0000, v181
	v_fmac_f32_e32 v105, v98, v100
	v_and_b32_e32 v98, 0xffff0000, v179
	v_fmac_f32_e32 v119, v99, v98
	v_mul_f32_e32 v98, v104, v104
	v_mul_f32_e32 v99, v119, v119
	v_fmac_f32_e32 v98, v103, v103
	v_fmac_f32_e32 v99, v105, v105
	v_add_f32_e32 v98, v98, v99
	v_add_f32_e32 v98, v98, v102
	ds_bpermute_b32 v99, v206, v98
	v_cvt_pk_bf16_f32 v107, v116, v117
	v_mov_b32_e32 v244, v106
	v_mov_b32_e32 v245, v107
	s_nop 1
	v_permlane16_swap_b32 v242, v244
	v_permlane16_swap_b32 v243, v245
	global_store_dwordx4 v[112:113], v[242:245], off
	v_cvt_pk_bf16_f32 v100, v108, v109
	v_cvt_pk_bf16_f32 v101, v110, v111
	s_waitcnt lgkmcnt(0)
	v_add_f32_e32 v98, v98, v99
	ds_bpermute_b32 v99, v207, v98
	v_mov_b32_e32 v242, v100
	v_mov_b32_e32 v243, v101
	v_cvt_pk_bf16_f32 v100, v103, v104
	v_cvt_pk_bf16_f32 v101, v105, v119
	v_mov_b32_e32 v244, v100
	v_mov_b32_e32 v245, v101
	s_nop 1
	v_permlane16_swap_b32 v242, v244
	v_permlane16_swap_b32 v243, v245
	global_store_dwordx4 v[112:113], v[242:245], off offset:256
	s_and_saveexec_b64 s[0:1], s[42:43]
	s_mov_b32 s28, 0xea00000
	s_movk_i32 s29, 0x2000
	s_cbranch_execz .LBB0_49
	s_waitcnt lgkmcnt(0)
	v_add_f32_e32 v98, v98, v99
	global_atomic_add_f32 v[114:115], v98, off offset:64
; __device__ __forceinline__ unsigned cvt_pk_bf16(float lo, float hi) { unsigned r; asm volatile("v_cvt_pk_bf16_f32 %0, %1, %2" : "=v"(r) : "v"(lo), "v"(hi)); return r; }
;     __device__ __forceinline__ void operator()(const f32x4 (&acc)[2][2][4][2], const Unit& u, int wr, int wc, int fr, int fq) const {
;     ...
;             for (int m = 0; m < 4; ++m) { const int row = row0 + ai * HALF + m * 16; const size_t ro = (size_t)row * 2048 + col0;
;                 float sc = 1.f; if (GATE) sc = rsqrtf(scv[m] * (1.f / 2048.f) + 1e-6f);
;                 float s = 0.f;
; #pragma unroll
;                 for (int bj = 0; bj < 2; ++bj)
; #pragma unroll
;                     for (int n = 0; n < 2; ++n) { const size_t p = ro + bj * HALF + n * 16; const u32x2e hh = hw[m][bj][n], pp = pw[m][bj][n]; const f32x4 a = acc[ai][bj][m][n];
;                         f32x4 h; h[0] = __uint_as_float(hh.x << 16); h[1] = __uint_as_float(hh.x & 0xffff0000u); h[2] = __uint_as_float(hh.y << 16); h[3] = __uint_as_float(hh.y & 0xffff0000u);
;                         if (GATE) {
;                             h[0] += __builtin_amdgcn_rcpf(1.f + __expf(-sc * a[0])) * __uint_as_float(pp.x << 16); h[1] += __builtin_amdgcn_rcpf(1.f + __expf(-sc * a[1])) * __uint_as_float(pp.x & 0xffff0000u);
;                             h[2] += __builtin_amdgcn_rcpf(1.f + __expf(-sc * a[2])) * __uint_as_float(pp.y << 16); h[3] += __builtin_amdgcn_rcpf(1.f + __expf(-sc * a[3])) * __uint_as_float(pp.y & 0xffff0000u); }
;                         else h = h + a;
;                         s += (h[0] * h[0] + h[1] * h[1]) + (h[2] * h[2] + h[3] * h[3]);
;                         u32x2e o; o.x = cvt_pk_bf16(h[0], h[1]); o.y = cvt_pk_bf16(h[2], h[3]); *(u32x2e*)(Hout + p) = o; }
;                 s += __shfl_xor(s, 16); s += __shfl_xor(s, 32);
;                 if (fq == 0) atomicAdd(rss_out + row, s); }
.LBB0_49:
	s_or_b64 exec, exec, s[0:1]
	v_fmamk_f32 v98, v240, 0x3a000000, v214
	s_waitcnt lgkmcnt(0)
	v_mul_f32_e32 v99, 0x4b800000, v98
	v_cmp_gt_f32_e32 vcc, s65, v98
	v_lshlrev_b32_e32 v101, 16, v174
	v_lshlrev_b32_e32 v105, 16, v172
	v_cndmask_b32_e32 v98, v98, v99, vcc
	v_rsq_f32_e32 v100, v98
	v_lshlrev_b32_e32 v103, 16, v175
	v_and_b32_e32 v104, 0xffff0000, v175
	v_lshlrev_b64 v[98:99], 12, v[176:177]
	v_mul_f32_e32 v102, 0x45800000, v100
	v_cndmask_b32_e32 v100, v100, v102, vcc
	v_mul_f32_e64 v94, v94, -v100
	v_mul_f32_e32 v94, 0x3fb8aa3b, v94
	v_exp_f32_e32 v94, v94
	v_mul_f32_e64 v95, v95, -v100
	v_mul_f32_e32 v95, 0x3fb8aa3b, v95
	v_exp_f32_e32 v95, v95
	v_add_f32_e32 v94, 1.0, v94
	v_rcp_f32_e32 v94, v94
	v_mul_f32_e64 v96, v96, -v100
	v_mul_f32_e32 v96, 0x3fb8aa3b, v96
	v_mul_f32_e64 v97, v97, -v100
	v_fmac_f32_e32 v101, v94, v105
	v_add_f32_e32 v94, 1.0, v95
	v_rcp_f32_e32 v94, v94
	v_exp_f32_e32 v96, v96
	v_mul_f32_e32 v97, 0x3fb8aa3b, v97
	v_exp_f32_e32 v97, v97
	v_and_b32_e32 v102, 0xffff0000, v174
	v_and_b32_e32 v95, 0xffff0000, v172
	v_fmac_f32_e32 v102, v94, v95
	v_add_f32_e32 v94, 1.0, v96
	v_mul_f32_e64 v90, v90, -v100
	v_rcp_f32_e32 v94, v94
	v_add_f32_e32 v95, 1.0, v97
	v_mul_f32_e32 v90, 0x3fb8aa3b, v90
	v_rcp_f32_e32 v95, v95
	v_exp_f32_e32 v90, v90
	v_lshlrev_b32_e32 v96, 16, v173
	v_fmac_f32_e32 v103, v94, v96
	v_and_b32_e32 v94, 0xffff0000, v173
	v_mul_f32_e64 v91, v91, -v100
	v_fmac_f32_e32 v104, v95, v94
	v_add_f32_e32 v90, 1.0, v90
	v_mul_f32_e32 v91, 0x3fb8aa3b, v91
	v_mul_f32_e32 v94, v102, v102
	v_mul_f32_e32 v95, v104, v104
	v_rcp_f32_e32 v90, v90
	v_exp_f32_e32 v91, v91
	v_fmac_f32_e32 v94, v101, v101
	v_fmac_f32_e32 v95, v103, v103
	v_lshl_add_u64 v[96:97], s[48:49], 0, v[98:99]
	v_add_f32_e32 v105, v94, v95
	v_cvt_pk_bf16_f32 v94, v101, v102
	v_lshl_add_u64 v[96:97], v[136:137], 1, v[96:97]
	v_cvt_pk_bf16_f32 v95, v103, v104
	v_add_u32_e32 v96, v250, v96
	v_mov_b32_e32 v242, v94
	v_mov_b32_e32 v243, v95
	v_lshlrev_b32_e32 v94, 16, v170
	v_lshlrev_b32_e32 v101, 16, v168
	v_mul_f32_e64 v92, v92, -v100
	v_fmac_f32_e32 v94, v90, v101
	v_add_f32_e32 v90, 1.0, v91
	v_mul_f32_e32 v92, 0x3fb8aa3b, v92
	v_mul_f32_e64 v86, v86, -v100
	v_rcp_f32_e32 v90, v90
	v_exp_f32_e32 v92, v92
	v_mul_f32_e32 v86, 0x3fb8aa3b, v86
	v_exp_f32_e32 v86, v86
	v_and_b32_e32 v95, 0xffff0000, v170
	v_and_b32_e32 v91, 0xffff0000, v168
	v_mul_f32_e64 v93, v93, -v100
	v_fmac_f32_e32 v95, v90, v91
	v_add_f32_e32 v90, 1.0, v92
	v_mul_f32_e64 v87, v87, -v100
	v_mul_f32_e32 v93, 0x3fb8aa3b, v93
	v_rcp_f32_e32 v90, v90
	v_add_f32_e32 v86, 1.0, v86
	v_mul_f32_e32 v87, 0x3fb8aa3b, v87
	v_exp_f32_e32 v93, v93
	v_rcp_f32_e32 v86, v86
	v_exp_f32_e32 v87, v87
	v_lshlrev_b32_e32 v98, 16, v171
	v_lshlrev_b32_e32 v92, 16, v169
	v_fmac_f32_e32 v98, v90, v92
	v_lshlrev_b32_e32 v92, 16, v166
	v_lshlrev_b32_e32 v101, 16, v164
	v_mul_f32_e64 v88, v88, -v100
	v_add_f32_e32 v91, 1.0, v93
	v_fmac_f32_e32 v92, v86, v101
	v_add_f32_e32 v86, 1.0, v87
	v_mul_f32_e32 v88, 0x3fb8aa3b, v88
	v_mul_f32_e64 v89, v89, -v100
	v_rcp_f32_e32 v91, v91
	v_rcp_f32_e32 v86, v86
	v_exp_f32_e32 v88, v88
	v_mul_f32_e32 v89, 0x3fb8aa3b, v89
	v_exp_f32_e32 v89, v89
	v_and_b32_e32 v99, 0xffff0000, v171
	v_and_b32_e32 v90, 0xffff0000, v169
	v_and_b32_e32 v93, 0xffff0000, v166
	v_and_b32_e32 v87, 0xffff0000, v164
	v_fmac_f32_e32 v99, v91, v90
	v_fmac_f32_e32 v93, v86, v87
	v_add_f32_e32 v86, 1.0, v88
	v_mul_f32_e64 v82, v82, -v100
	v_mul_f32_e32 v90, v95, v95
	v_mul_f32_e32 v91, v99, v99
	v_rcp_f32_e32 v86, v86
	v_add_f32_e32 v87, 1.0, v89
	v_mul_f32_e32 v82, 0x3fb8aa3b, v82
	v_fmac_f32_e32 v90, v94, v94
	v_fmac_f32_e32 v91, v98, v98
	v_rcp_f32_e32 v87, v87
	v_exp_f32_e32 v82, v82
	v_add_f32_e32 v90, v90, v91
	v_add_f32_e32 v91, v105, v90
	v_cvt_pk_bf16_f32 v90, v94, v95
	v_lshlrev_b32_e32 v94, 16, v167
	v_lshlrev_b32_e32 v88, 16, v165
	v_and_b32_e32 v95, 0xffff0000, v167
	v_fmac_f32_e32 v94, v86, v88
	v_and_b32_e32 v86, 0xffff0000, v165
	v_mul_f32_e64 v83, v83, -v100
	v_fmac_f32_e32 v95, v87, v86
	v_add_f32_e32 v82, 1.0, v82
	v_mul_f32_e32 v83, 0x3fb8aa3b, v83
	v_mul_f32_e32 v86, v93, v93
	v_mul_f32_e32 v87, v95, v95
	v_rcp_f32_e32 v82, v82
	v_exp_f32_e32 v83, v83
	v_fmac_f32_e32 v86, v92, v92
	v_fmac_f32_e32 v87, v94, v94
	v_add_f32_e32 v86, v86, v87
	v_add_f32_e32 v86, v86, v91
	v_lshlrev_b32_e32 v87, 16, v162
	v_lshlrev_b32_e32 v91, 16, v160
	v_mul_f32_e64 v84, v84, -v100
	v_fmac_f32_e32 v87, v82, v91
	v_add_f32_e32 v82, 1.0, v83
	v_mul_f32_e32 v84, 0x3fb8aa3b, v84
	v_mul_f32_e64 v85, v85, -v100
	v_rcp_f32_e32 v82, v82
	v_exp_f32_e32 v84, v84
	v_mul_f32_e32 v85, 0x3fb8aa3b, v85
	v_exp_f32_e32 v85, v85
	v_and_b32_e32 v88, 0xffff0000, v162
	v_and_b32_e32 v83, 0xffff0000, v160
	v_fmac_f32_e32 v88, v82, v83
	v_add_f32_e32 v82, 1.0, v84
	v_rcp_f32_e32 v82, v82
	v_add_f32_e32 v83, 1.0, v85
	v_rcp_f32_e32 v83, v83
	v_lshlrev_b32_e32 v89, 16, v163
	v_lshlrev_b32_e32 v84, 16, v161
	v_and_b32_e32 v101, 0xffff0000, v163
	v_fmac_f32_e32 v89, v82, v84
	v_and_b32_e32 v82, 0xffff0000, v161
	v_fmac_f32_e32 v101, v83, v82
	v_mul_f32_e32 v82, v88, v88
	v_mul_f32_e32 v83, v101, v101
	v_fmac_f32_e32 v82, v87, v87
	v_fmac_f32_e32 v83, v89, v89
	v_add_f32_e32 v82, v82, v83
	v_add_f32_e32 v82, v82, v86
	ds_bpermute_b32 v83, v206, v82
	v_cvt_pk_bf16_f32 v91, v98, v99
	v_mov_b32_e32 v244, v90
	v_mov_b32_e32 v245, v91
	s_nop 1
	v_permlane16_swap_b32 v242, v244
	v_permlane16_swap_b32 v243, v245
	global_store_dwordx4 v[96:97], v[242:245], off
	v_cvt_pk_bf16_f32 v84, v92, v93
	v_cvt_pk_bf16_f32 v85, v94, v95
	s_waitcnt lgkmcnt(0)
	v_add_f32_e32 v82, v82, v83
	ds_bpermute_b32 v83, v207, v82
	v_mov_b32_e32 v242, v84
	v_mov_b32_e32 v243, v85
	v_cvt_pk_bf16_f32 v84, v87, v88
	v_cvt_pk_bf16_f32 v85, v89, v101
	v_mov_b32_e32 v244, v84
	v_mov_b32_e32 v245, v85
	s_nop 1
	v_permlane16_swap_b32 v242, v244
	v_permlane16_swap_b32 v243, v245
	global_store_dwordx4 v[96:97], v[242:245], off offset:256
	s_and_saveexec_b64 s[0:1], s[42:43]
	s_cbranch_execz .LBB0_51
	s_waitcnt lgkmcnt(0)
	v_add_f32_e32 v82, v82, v83
	global_atomic_add_f32 v[114:115], v82, off offset:128
; __device__ __forceinline__ unsigned cvt_pk_bf16(float lo, float hi) { unsigned r; asm volatile("v_cvt_pk_bf16_f32 %0, %1, %2" : "=v"(r) : "v"(lo), "v"(hi)); return r; }
;     __device__ __forceinline__ void operator()(const f32x4 (&acc)[2][2][4][2], const Unit& u, int wr, int wc, int fr, int fq) const {
;     ...
;             for (int m = 0; m < 4; ++m) { const int row = row0 + ai * HALF + m * 16; const size_t ro = (size_t)row * 2048 + col0;
;                 float sc = 1.f; if (GATE) sc = rsqrtf(scv[m] * (1.f / 2048.f) + 1e-6f);
;                 float s = 0.f;
; #pragma unroll
;                 for (int bj = 0; bj < 2; ++bj)
; #pragma unroll
;                     for (int n = 0; n < 2; ++n) { const size_t p = ro + bj * HALF + n * 16; const u32x2e hh = hw[m][bj][n], pp = pw[m][bj][n]; const f32x4 a = acc[ai][bj][m][n];
;                         f32x4 h; h[0] = __uint_as_float(hh.x << 16); h[1] = __uint_as_float(hh.x & 0xffff0000u); h[2] = __uint_as_float(hh.y << 16); h[3] = __uint_as_float(hh.y & 0xffff0000u);
;                         if (GATE) {
;                             h[0] += __builtin_amdgcn_rcpf(1.f + __expf(-sc * a[0])) * __uint_as_float(pp.x << 16); h[1] += __builtin_amdgcn_rcpf(1.f + __expf(-sc * a[1])) * __uint_as_float(pp.x & 0xffff0000u);
;                             h[2] += __builtin_amdgcn_rcpf(1.f + __expf(-sc * a[2])) * __uint_as_float(pp.y << 16); h[3] += __builtin_amdgcn_rcpf(1.f + __expf(-sc * a[3])) * __uint_as_float(pp.y & 0xffff0000u); }
;                         else h = h + a;
;                         s += (h[0] * h[0] + h[1] * h[1]) + (h[2] * h[2] + h[3] * h[3]);
;                         u32x2e o; o.x = cvt_pk_bf16(h[0], h[1]); o.y = cvt_pk_bf16(h[2], h[3]); *(u32x2e*)(Hout + p) = o; }
;                 s += __shfl_xor(s, 16); s += __shfl_xor(s, 32);
;                 if (fq == 0) atomicAdd(rss_out + row, s); }
.LBB0_51:
	s_or_b64 exec, exec, s[0:1]
	v_fmamk_f32 v82, v239, 0x3a000000, v214
	s_waitcnt lgkmcnt(0)
	v_mul_f32_e32 v83, 0x4b800000, v82
	v_cmp_gt_f32_e32 vcc, s65, v82
	v_lshlrev_b32_e32 v85, 16, v156
	v_lshlrev_b32_e32 v89, 16, v154
	v_cndmask_b32_e32 v82, v82, v83, vcc
	v_rsq_f32_e32 v84, v82
	v_lshlrev_b32_e32 v87, 16, v157
	v_and_b32_e32 v88, 0xffff0000, v157
	v_lshlrev_b64 v[82:83], 12, v[158:159]
	v_mul_f32_e32 v86, 0x45800000, v84
	v_cndmask_b32_e32 v84, v84, v86, vcc
	v_mul_f32_e64 v78, v78, -v84
	v_mul_f32_e32 v78, 0x3fb8aa3b, v78
	v_exp_f32_e32 v78, v78
	v_mul_f32_e64 v79, v79, -v84
	v_mul_f32_e32 v79, 0x3fb8aa3b, v79
	v_exp_f32_e32 v79, v79
	v_add_f32_e32 v78, 1.0, v78
	v_rcp_f32_e32 v78, v78
	v_mul_f32_e64 v80, v80, -v84
	v_mul_f32_e32 v80, 0x3fb8aa3b, v80
	v_mul_f32_e64 v81, v81, -v84
	v_fmac_f32_e32 v85, v78, v89
	v_add_f32_e32 v78, 1.0, v79
	v_rcp_f32_e32 v78, v78
	v_exp_f32_e32 v80, v80
	v_mul_f32_e32 v81, 0x3fb8aa3b, v81
	v_exp_f32_e32 v81, v81
	v_and_b32_e32 v86, 0xffff0000, v156
	v_and_b32_e32 v79, 0xffff0000, v154
	v_fmac_f32_e32 v86, v78, v79
	v_add_f32_e32 v78, 1.0, v80
	v_mul_f32_e64 v74, v74, -v84
	v_rcp_f32_e32 v78, v78
	v_add_f32_e32 v79, 1.0, v81
	v_mul_f32_e32 v74, 0x3fb8aa3b, v74
	v_rcp_f32_e32 v79, v79
	v_exp_f32_e32 v74, v74
	v_lshlrev_b32_e32 v80, 16, v155
	v_fmac_f32_e32 v87, v78, v80
	v_and_b32_e32 v78, 0xffff0000, v155
	v_mul_f32_e64 v75, v75, -v84
	v_fmac_f32_e32 v88, v79, v78
	v_add_f32_e32 v74, 1.0, v74
	v_mul_f32_e32 v75, 0x3fb8aa3b, v75
	v_mul_f32_e32 v78, v86, v86
	v_mul_f32_e32 v79, v88, v88
	v_rcp_f32_e32 v74, v74
	v_exp_f32_e32 v75, v75
	v_fmac_f32_e32 v78, v85, v85
	v_fmac_f32_e32 v79, v87, v87
	v_lshl_add_u64 v[80:81], s[48:49], 0, v[82:83]
	v_add_f32_e32 v89, v78, v79
	v_cvt_pk_bf16_f32 v78, v85, v86
	v_lshl_add_u64 v[80:81], v[136:137], 1, v[80:81]
	v_cvt_pk_bf16_f32 v79, v87, v88
	v_add_u32_e32 v80, v250, v80
	v_mov_b32_e32 v242, v78
	v_mov_b32_e32 v243, v79
	v_lshlrev_b32_e32 v78, 16, v152
	v_lshlrev_b32_e32 v85, 16, v150
	v_mul_f32_e64 v76, v76, -v84
	v_fmac_f32_e32 v78, v74, v85
	v_add_f32_e32 v74, 1.0, v75
	v_mul_f32_e32 v76, 0x3fb8aa3b, v76
	v_mul_f32_e64 v70, v70, -v84
	v_rcp_f32_e32 v74, v74
	v_exp_f32_e32 v76, v76
	v_mul_f32_e32 v70, 0x3fb8aa3b, v70
	v_exp_f32_e32 v70, v70
	v_and_b32_e32 v79, 0xffff0000, v152
	v_and_b32_e32 v75, 0xffff0000, v150
	v_mul_f32_e64 v77, v77, -v84
	v_fmac_f32_e32 v79, v74, v75
	v_add_f32_e32 v74, 1.0, v76
	v_mul_f32_e64 v71, v71, -v84
	v_mul_f32_e32 v77, 0x3fb8aa3b, v77
	v_rcp_f32_e32 v74, v74
	v_add_f32_e32 v70, 1.0, v70
	v_mul_f32_e32 v71, 0x3fb8aa3b, v71
	v_exp_f32_e32 v77, v77
	v_rcp_f32_e32 v70, v70
	v_exp_f32_e32 v71, v71
	v_lshlrev_b32_e32 v82, 16, v153
	v_lshlrev_b32_e32 v76, 16, v151
	v_fmac_f32_e32 v82, v74, v76
	v_lshlrev_b32_e32 v76, 16, v148
	s_waitcnt vmcnt(15)
	v_lshlrev_b32_e32 v85, 16, v146
	v_mul_f32_e64 v72, v72, -v84
	v_add_f32_e32 v75, 1.0, v77
	v_fmac_f32_e32 v76, v70, v85
	v_add_f32_e32 v70, 1.0, v71
	v_mul_f32_e32 v72, 0x3fb8aa3b, v72
	v_mul_f32_e64 v73, v73, -v84
	v_rcp_f32_e32 v75, v75
	v_rcp_f32_e32 v70, v70
	v_exp_f32_e32 v72, v72
	v_mul_f32_e32 v73, 0x3fb8aa3b, v73
	v_exp_f32_e32 v73, v73
	v_and_b32_e32 v83, 0xffff0000, v153
	v_and_b32_e32 v74, 0xffff0000, v151
	v_and_b32_e32 v77, 0xffff0000, v148
	v_and_b32_e32 v71, 0xffff0000, v146
	v_fmac_f32_e32 v83, v75, v74
	v_fmac_f32_e32 v77, v70, v71
	v_add_f32_e32 v70, 1.0, v72
	v_mul_f32_e64 v66, v66, -v84
	v_mul_f32_e32 v74, v79, v79
	v_mul_f32_e32 v75, v83, v83
	v_rcp_f32_e32 v70, v70
	v_add_f32_e32 v71, 1.0, v73
	v_mul_f32_e32 v66, 0x3fb8aa3b, v66
	v_fmac_f32_e32 v74, v78, v78
	v_fmac_f32_e32 v75, v82, v82
	v_rcp_f32_e32 v71, v71
	v_exp_f32_e32 v66, v66
	v_add_f32_e32 v74, v74, v75
	v_add_f32_e32 v75, v89, v74
	v_cvt_pk_bf16_f32 v74, v78, v79
	v_lshlrev_b32_e32 v78, 16, v149
	v_lshlrev_b32_e32 v72, 16, v147
	v_and_b32_e32 v79, 0xffff0000, v149
	v_fmac_f32_e32 v78, v70, v72
	v_and_b32_e32 v70, 0xffff0000, v147
	v_mul_f32_e64 v67, v67, -v84
	v_fmac_f32_e32 v79, v71, v70
	v_add_f32_e32 v66, 1.0, v66
	v_mul_f32_e32 v67, 0x3fb8aa3b, v67
	v_mul_f32_e32 v70, v77, v77
	v_mul_f32_e32 v71, v79, v79
	v_rcp_f32_e32 v66, v66
	v_exp_f32_e32 v67, v67
	v_fmac_f32_e32 v70, v76, v76
	v_fmac_f32_e32 v71, v78, v78
	v_add_f32_e32 v70, v70, v71
	v_add_f32_e32 v70, v70, v75
	s_waitcnt vmcnt(14)
	v_lshlrev_b32_e32 v71, 16, v144
	s_waitcnt vmcnt(13)
	v_lshlrev_b32_e32 v75, 16, v142
	v_mul_f32_e64 v68, v68, -v84
	v_fmac_f32_e32 v71, v66, v75
	v_add_f32_e32 v66, 1.0, v67
	v_mul_f32_e32 v68, 0x3fb8aa3b, v68
	v_mul_f32_e64 v69, v69, -v84
	v_rcp_f32_e32 v66, v66
	v_exp_f32_e32 v68, v68
	v_mul_f32_e32 v69, 0x3fb8aa3b, v69
	v_exp_f32_e32 v69, v69
	v_and_b32_e32 v72, 0xffff0000, v144
	v_and_b32_e32 v67, 0xffff0000, v142
	v_fmac_f32_e32 v72, v66, v67
	v_add_f32_e32 v66, 1.0, v68
	v_rcp_f32_e32 v66, v66
	v_add_f32_e32 v67, 1.0, v69
	v_rcp_f32_e32 v67, v67
	v_lshlrev_b32_e32 v73, 16, v145
	v_lshlrev_b32_e32 v68, 16, v143
	v_and_b32_e32 v85, 0xffff0000, v145
	v_fmac_f32_e32 v73, v66, v68
	v_and_b32_e32 v66, 0xffff0000, v143
	v_fmac_f32_e32 v85, v67, v66
	v_mul_f32_e32 v66, v72, v72
	v_mul_f32_e32 v67, v85, v85
	v_fmac_f32_e32 v66, v71, v71
	v_fmac_f32_e32 v67, v73, v73
	v_add_f32_e32 v66, v66, v67
	v_add_f32_e32 v66, v66, v70
	ds_bpermute_b32 v67, v206, v66
	v_cvt_pk_bf16_f32 v75, v82, v83
	v_mov_b32_e32 v244, v74
	v_mov_b32_e32 v245, v75
	s_nop 1
	v_permlane16_swap_b32 v242, v244
	v_permlane16_swap_b32 v243, v245
	global_store_dwordx4 v[80:81], v[242:245], off
	v_cvt_pk_bf16_f32 v68, v76, v77
	v_cvt_pk_bf16_f32 v69, v78, v79
	s_waitcnt lgkmcnt(0)
	v_add_f32_e32 v66, v66, v67
	ds_bpermute_b32 v67, v207, v66
	v_mov_b32_e32 v242, v68
	v_mov_b32_e32 v243, v69
	v_cvt_pk_bf16_f32 v68, v71, v72
	v_cvt_pk_bf16_f32 v69, v73, v85
	v_mov_b32_e32 v244, v68
	v_mov_b32_e32 v245, v69
	s_nop 1
	v_permlane16_swap_b32 v242, v244
	v_permlane16_swap_b32 v243, v245
	global_store_dwordx4 v[80:81], v[242:245], off offset:256
	s_and_saveexec_b64 s[0:1], s[42:43]
	s_movk_i32 s30, 0x104
	s_mov_b32 s31, 0x22200000
	s_cbranch_execz .LBB0_53
	s_waitcnt lgkmcnt(0)
	v_add_f32_e32 v66, v66, v67
	global_atomic_add_f32 v[114:115], v66, off offset:192
;     __device__ __forceinline__ void operator()(const f32x4 (&acc)[2][2][4][2], const Unit& u, int wr, int wc, int fr, int fq) const {
;     ...
;             for (int m = 0; m < 4; ++m) { const int row = row0 + ai * HALF + m * 16; const size_t ro = (size_t)row * 2048 + col0;
;                 scv[m] = GATE ? rss_in[row] : 0.f;
; #pragma unroll
;                 for (int bj = 0; bj < 2; ++bj)
; #pragma unroll
;                     for (int n = 0; n < 2; ++n) { const size_t p = ro + bj * HALF + n * 16; hw[m][bj][n] = *(const u32x2e*)(Hin + p); if (GATE) pw[m][bj][n] = *(const u32x2e*)(PP + p); else pw[m][bj][n] = (u32x2e){0u, 0u}; } }
; #pragma unroll
;             for (int m = 0; m < 4; ++m) { const int row = row0 + ai * HALF + m * 16; const size_t ro = (size_t)row * 2048 + col0;
;                 float sc = 1.f; if (GATE) sc = rsqrtf(scv[m] * (1.f / 2048.f) + 1e-6f);
;                 float s = 0.f;
; #pragma unroll
;                 for (int bj = 0; bj < 2; ++bj)
; #pragma unroll
;                     for (int n = 0; n < 2; ++n) { const size_t p = ro + bj * HALF + n * 16; const u32x2e hh = hw[m][bj][n], pp = pw[m][bj][n]; const f32x4 a = acc[ai][bj][m][n];
;                         f32x4 h; h[0] = __uint_as_float(hh.x << 16); h[1] = __uint_as_float(hh.x & 0xffff0000u); h[2] = __uint_as_float(hh.y << 16); h[3] = __uint_as_float(hh.y & 0xffff0000u);
;                         if (GATE) {
;                             h[0] += __builtin_amdgcn_rcpf(1.f + __expf(-sc * a[0])) * __uint_as_float(pp.x << 16); h[1] += __builtin_amdgcn_rcpf(1.f + __expf(-sc * a[1])) * __uint_as_float(pp.x & 0xffff0000u);
;                             h[2] += __builtin_amdgcn_rcpf(1.f + __expf(-sc * a[2])) * __uint_as_float(pp.y << 16); h[3] += __builtin_amdgcn_rcpf(1.f + __expf(-sc * a[3])) * __uint_as_float(pp.y & 0xffff0000u); }
.LBB0_53:
	s_or_b64 exec, exec, s[0:1]
	s_waitcnt vmcnt(8)
	s_barrier
	v_add_u32_e32 v144, 0x80, v138
	v_ashrrev_i32_e32 v145, 31, v144
	s_waitcnt lgkmcnt(0)
	v_lshlrev_b64 v[66:67], 11, v[144:145]
	v_lshl_add_u64 v[66:67], v[66:67], 0, v[136:137]
	v_lshlrev_b64 v[66:67], 1, v[66:67]
	v_lshl_add_u64 v[68:69], s[46:47], 0, v[66:67]
	global_load_dword v143, v[140:141], off offset:512
	ds_read_b64 v[146:147], v130 offset:0
	v_lshl_add_u64 v[68:69], s[52:53], 0, v[66:67]
	v_or_b32_e32 v70, 32, v66
	v_mov_b32_e32 v71, v67
	v_or_b32_e32 v74, 0x100, v66
	v_mov_b32_e32 v75, v67
	v_lshl_add_u64 v[72:73], s[46:47], 0, v[70:71]
	v_lshl_add_u64 v[70:71], s[52:53], 0, v[70:71]
	v_lshl_add_u64 v[76:77], s[46:47], 0, v[74:75]
	ds_read_b64 v[148:149], v132 offset:0
	ds_read_b64 v[150:151], v131 offset:0
	ds_read_b64 v[152:153], v133 offset:0
	ds_read_b64 v[128:129], v130 offset:256
	v_add_u32_e32 v120, 0x90, v138
	v_ashrrev_i32_e32 v121, 31, v120
	v_lshlrev_b64 v[72:73], 11, v[120:121]
	v_lshl_add_u64 v[72:73], v[72:73], 0, v[136:137]
	v_lshl_add_u64 v[68:69], s[52:53], 0, v[74:75]
	v_or_b32_e32 v66, 0x120, v66
	v_lshlrev_b64 v[72:73], 1, v[72:73]
	v_lshl_add_u64 v[70:71], s[46:47], 0, v[66:67]
	v_lshl_add_u64 v[66:67], s[52:53], 0, v[66:67]
	v_lshl_add_u64 v[74:75], s[46:47], 0, v[72:73]
	ds_read_b64 v[126:127], v132 offset:256
	ds_read_b64 v[124:125], v131 offset:256
	ds_read_b64 v[122:123], v133 offset:256
	ds_read_b64 v[118:119], v130 offset:8192
	v_or_b32_e32 v68, 32, v72
	v_mov_b32_e32 v69, v73
	v_add_u32_e32 v100, 0xa0, v138
	v_lshl_add_u64 v[66:67], s[52:53], 0, v[72:73]
	v_lshl_add_u64 v[70:71], s[46:47], 0, v[68:69]
	v_lshl_add_u64 v[68:69], s[52:53], 0, v[68:69]
	v_or_b32_e32 v74, 0x100, v72
	v_mov_b32_e32 v75, v73
	v_or_b32_e32 v72, 0x120, v72
	v_ashrrev_i32_e32 v101, 31, v100
	v_lshl_add_u64 v[76:77], s[46:47], 0, v[74:75]
	ds_read_b64 v[116:117], v132 offset:8192
	ds_read_b64 v[112:113], v131 offset:8192
	ds_read_b64 v[110:111], v133 offset:8192
	ds_read_b64 v[108:109], v130 offset:8448
	v_lshl_add_u64 v[68:69], s[46:47], 0, v[72:73]
	v_lshl_add_u64 v[70:71], s[52:53], 0, v[72:73]
	v_lshlrev_b64 v[72:73], 11, v[100:101]
	v_lshl_add_u64 v[72:73], v[72:73], 0, v[136:137]
	v_lshl_add_u64 v[66:67], s[52:53], 0, v[74:75]
	v_lshlrev_b64 v[72:73], 1, v[72:73]
	v_lshl_add_u64 v[74:75], s[46:47], 0, v[72:73]
	ds_read_b64 v[106:107], v132 offset:8448
	ds_read_b64 v[104:105], v131 offset:8448
	ds_read_b64 v[102:103], v133 offset:8448
	ds_read_b64 v[98:99], v130 offset:16384
	v_or_b32_e32 v68, 32, v72
	v_mov_b32_e32 v69, v73
	v_add_u32_e32 v82, 0xb0, v138
	v_lshl_add_u64 v[66:67], s[52:53], 0, v[72:73]
	v_lshl_add_u64 v[70:71], s[46:47], 0, v[68:69]
	v_lshl_add_u64 v[68:69], s[52:53], 0, v[68:69]
	v_or_b32_e32 v74, 0x100, v72
	v_mov_b32_e32 v75, v73
	v_or_b32_e32 v72, 0x120, v72
	v_ashrrev_i32_e32 v83, 31, v82
	v_lshl_add_u64 v[76:77], s[46:47], 0, v[74:75]
	ds_read_b64 v[96:97], v132 offset:16384
	ds_read_b64 v[94:95], v131 offset:16384
	ds_read_b64 v[92:93], v133 offset:16384
	ds_read_b64 v[90:91], v130 offset:16640
	v_lshl_add_u64 v[68:69], s[46:47], 0, v[72:73]
	v_lshl_add_u64 v[70:71], s[52:53], 0, v[72:73]
	v_lshlrev_b64 v[72:73], 11, v[82:83]
	v_lshl_add_u64 v[72:73], v[72:73], 0, v[136:137]
	v_lshl_add_u64 v[66:67], s[52:53], 0, v[74:75]
	global_load_dword v142, v[140:141], off offset:576
	global_load_dword v139, v[140:141], off offset:640
	global_load_dword v138, v[140:141], off offset:704
	v_lshlrev_b64 v[140:141], 1, v[72:73]
	v_lshl_add_u64 v[72:73], s[46:47], 0, v[140:141]
	ds_read_b64 v[88:89], v132 offset:16640
	ds_read_b64 v[86:87], v131 offset:16640
	ds_read_b64 v[84:85], v133 offset:16640
	ds_read_b64 v[80:81], v130 offset:24576
	v_or_b32_e32 v68, 32, v140
	v_mov_b32_e32 v69, v141
	v_or_b32_e32 v154, 0x100, v140
	v_mov_b32_e32 v155, v141
	v_lshl_add_u64 v[66:67], s[52:53], 0, v[140:141]
	v_lshl_add_u64 v[70:71], s[46:47], 0, v[68:69]
	v_lshl_add_u64 v[72:73], s[46:47], 0, v[154:155]
	v_lshl_add_u64 v[68:69], s[52:53], 0, v[68:69]
	ds_read_b64 v[78:79], v132 offset:24576
	ds_read_b64 v[76:77], v131 offset:24576
	ds_read_b64 v[74:75], v133 offset:24576
	s_nop 0
	ds_read_b64 v[72:73], v130 offset:24832
	v_or_b32_e32 v140, 0x120, v140
	v_lshl_add_u64 v[66:67], s[52:53], 0, v[154:155]
	v_lshl_add_u64 v[68:69], s[46:47], 0, v[140:141]
	v_lshl_add_u64 v[140:141], s[52:53], 0, v[140:141]
	s_waitcnt vmcnt(0) lgkmcnt(0)
	v_fmamk_f32 v70, v143, 0x3a000000, v214
	v_mul_f32_e32 v71, 0x4b800000, v70
	v_cmp_gt_f32_e32 vcc, s65, v70
	s_waitcnt vmcnt(0) lgkmcnt(0)
	v_lshlrev_b32_e32 v154, 16, v148
	v_cndmask_b32_e32 v70, v70, v71, vcc
	v_rsq_f32_e32 v143, v70
	ds_read_b64 v[70:71], v132 offset:24832
	s_nop 0
	ds_read_b64 v[68:69], v131 offset:24832
	s_nop 0
	ds_read_b64 v[66:67], v133 offset:24832
	s_waitcnt vmcnt(0) lgkmcnt(0)
; __device__ __forceinline__ unsigned cvt_pk_bf16(float lo, float hi) { unsigned r; asm volatile("v_cvt_pk_bf16_f32 %0, %1, %2" : "=v"(r) : "v"(lo), "v"(hi)); return r; }
;     __device__ __forceinline__ void operator()(const f32x4 (&acc)[2][2][4][2], const Unit& u, int wr, int wc, int fr, int fq) const {
;     ...
;             for (int m = 0; m < 4; ++m) { const int row = row0 + ai * HALF + m * 16; const size_t ro = (size_t)row * 2048 + col0;
;                 float sc = 1.f; if (GATE) sc = rsqrtf(scv[m] * (1.f / 2048.f) + 1e-6f);
;                 float s = 0.f;
; #pragma unroll
;                 for (int bj = 0; bj < 2; ++bj)
; #pragma unroll
;                     for (int n = 0; n < 2; ++n) { const size_t p = ro + bj * HALF + n * 16; const u32x2e hh = hw[m][bj][n], pp = pw[m][bj][n]; const f32x4 a = acc[ai][bj][m][n];
;                         f32x4 h; h[0] = __uint_as_float(hh.x << 16); h[1] = __uint_as_float(hh.x & 0xffff0000u); h[2] = __uint_as_float(hh.y << 16); h[3] = __uint_as_float(hh.y & 0xffff0000u);
;                         if (GATE) {
;                             h[0] += __builtin_amdgcn_rcpf(1.f + __expf(-sc * a[0])) * __uint_as_float(pp.x << 16); h[1] += __builtin_amdgcn_rcpf(1.f + __expf(-sc * a[1])) * __uint_as_float(pp.x & 0xffff0000u);
;                             h[2] += __builtin_amdgcn_rcpf(1.f + __expf(-sc * a[2])) * __uint_as_float(pp.y << 16); h[3] += __builtin_amdgcn_rcpf(1.f + __expf(-sc * a[3])) * __uint_as_float(pp.y & 0xffff0000u); }
;                         else h = h + a;
;                         s += (h[0] * h[0] + h[1] * h[1]) + (h[2] * h[2] + h[3] * h[3]);
;                         u32x2e o; o.x = cvt_pk_bf16(h[0], h[1]); o.y = cvt_pk_bf16(h[2], h[3]); *(u32x2e*)(Hout + p) = o; }
;                 s += __shfl_xor(s, 16); s += __shfl_xor(s, 32);
;                 if (fq == 0) atomicAdd(rss_out + row, s); }
	v_mul_f32_e32 v140, 0x45800000, v143
	v_cndmask_b32_e32 v143, v143, v140, vcc
	v_mul_f32_e64 v62, v62, -v143
	v_mul_f32_e32 v62, 0x3fb8aa3b, v62
	v_exp_f32_e32 v62, v62
	v_mul_f32_e64 v63, v63, -v143
	v_mul_f32_e32 v63, 0x3fb8aa3b, v63
	v_exp_f32_e32 v63, v63
	v_add_f32_e32 v62, 1.0, v62
	v_rcp_f32_e32 v62, v62
	v_lshlrev_b64 v[140:141], 12, v[144:145]
	v_lshlrev_b32_e32 v144, 16, v146
	v_mul_f32_e64 v64, v64, -v143
	v_fmac_f32_e32 v144, v62, v154
	v_add_f32_e32 v62, 1.0, v63
	v_mul_f32_e32 v64, 0x3fb8aa3b, v64
	v_mul_f32_e64 v65, v65, -v143
	v_rcp_f32_e32 v62, v62
	v_exp_f32_e32 v64, v64
	v_mul_f32_e32 v65, 0x3fb8aa3b, v65
	v_exp_f32_e32 v65, v65
	v_and_b32_e32 v145, 0xffff0000, v146
	v_and_b32_e32 v63, 0xffff0000, v148
	v_fmac_f32_e32 v145, v62, v63
	v_add_f32_e32 v62, 1.0, v64
	v_mul_f32_e64 v58, v58, -v143
	v_rcp_f32_e32 v62, v62
	v_add_f32_e32 v63, 1.0, v65
	v_mul_f32_e32 v58, 0x3fb8aa3b, v58
	v_rcp_f32_e32 v63, v63
	v_exp_f32_e32 v58, v58
	v_lshlrev_b32_e32 v146, 16, v147
	v_lshlrev_b32_e32 v64, 16, v149
	v_and_b32_e32 v147, 0xffff0000, v147
	v_fmac_f32_e32 v146, v62, v64
	v_and_b32_e32 v62, 0xffff0000, v149
	v_mul_f32_e64 v59, v59, -v143
	v_fmac_f32_e32 v147, v63, v62
	v_add_f32_e32 v58, 1.0, v58
	v_mul_f32_e32 v59, 0x3fb8aa3b, v59
	v_mul_f32_e32 v62, v145, v145
	v_mul_f32_e32 v63, v147, v147
	v_rcp_f32_e32 v58, v58
	v_exp_f32_e32 v59, v59
	v_fmac_f32_e32 v62, v144, v144
	v_fmac_f32_e32 v63, v146, v146
	v_lshl_add_u64 v[64:65], s[48:49], 0, v[140:141]
	v_add_f32_e32 v148, v62, v63
	v_cvt_pk_bf16_f32 v62, v144, v145
	v_lshl_add_u64 v[64:65], v[136:137], 1, v[64:65]
	v_cvt_pk_bf16_f32 v63, v146, v147
	v_add_u32_e32 v64, v250, v64
	v_mov_b32_e32 v242, v62
	v_mov_b32_e32 v243, v63
	s_waitcnt vmcnt(33)
	v_lshlrev_b32_e32 v62, 16, v150
	s_waitcnt vmcnt(32)
	v_lshlrev_b32_e32 v144, 16, v152
	v_mul_f32_e64 v60, v60, -v143
	v_fmac_f32_e32 v62, v58, v144
	v_add_f32_e32 v58, 1.0, v59
	v_mul_f32_e32 v60, 0x3fb8aa3b, v60
	v_mul_f32_e64 v54, v54, -v143
	v_rcp_f32_e32 v58, v58
	v_exp_f32_e32 v60, v60
	v_mul_f32_e32 v54, 0x3fb8aa3b, v54
	v_exp_f32_e32 v54, v54
	v_and_b32_e32 v63, 0xffff0000, v150
	v_and_b32_e32 v59, 0xffff0000, v152
	v_mul_f32_e64 v61, v61, -v143
	v_mul_f32_e32 v61, 0x3fb8aa3b, v61
	v_fmac_f32_e32 v63, v58, v59
	v_add_f32_e32 v58, 1.0, v60
	v_mul_f32_e64 v55, v55, -v143
	v_exp_f32_e32 v61, v61
	v_rcp_f32_e32 v58, v58
	v_add_f32_e32 v54, 1.0, v54
	v_mul_f32_e32 v55, 0x3fb8aa3b, v55
	v_rcp_f32_e32 v54, v54
	v_exp_f32_e32 v55, v55
	v_lshlrev_b32_e32 v140, 16, v151
	v_lshlrev_b32_e32 v60, 16, v153
	v_add_f32_e32 v59, 1.0, v61
	v_fmac_f32_e32 v140, v58, v60
	s_waitcnt vmcnt(31)
	v_lshlrev_b32_e32 v60, 16, v128
	v_and_b32_e32 v61, 0xffff0000, v128
	s_waitcnt vmcnt(30)
	v_lshlrev_b32_e32 v128, 16, v126
	v_mul_f32_e64 v56, v56, -v143
	v_fmac_f32_e32 v60, v54, v128
	v_add_f32_e32 v54, 1.0, v55
	v_mul_f32_e32 v56, 0x3fb8aa3b, v56
	v_mul_f32_e64 v57, v57, -v143
	v_rcp_f32_e32 v59, v59
	v_rcp_f32_e32 v54, v54
	v_exp_f32_e32 v56, v56
	v_mul_f32_e32 v57, 0x3fb8aa3b, v57
	v_exp_f32_e32 v57, v57
	v_and_b32_e32 v141, 0xffff0000, v151
	v_and_b32_e32 v58, 0xffff0000, v153
	v_and_b32_e32 v55, 0xffff0000, v126
	v_fmac_f32_e32 v141, v59, v58
	v_fmac_f32_e32 v61, v54, v55
	v_add_f32_e32 v54, 1.0, v56
	v_mul_f32_e64 v50, v50, -v143
	v_mul_f32_e32 v58, v63, v63
	v_mul_f32_e32 v59, v141, v141
	v_rcp_f32_e32 v54, v54
	v_add_f32_e32 v55, 1.0, v57
	v_mul_f32_e32 v50, 0x3fb8aa3b, v50
	v_fmac_f32_e32 v58, v62, v62
	v_fmac_f32_e32 v59, v140, v140
	v_rcp_f32_e32 v55, v55
	v_exp_f32_e32 v50, v50
	v_add_f32_e32 v58, v58, v59
	v_add_f32_e32 v59, v148, v58
	v_cvt_pk_bf16_f32 v58, v62, v63
	v_lshlrev_b32_e32 v62, 16, v129
	v_lshlrev_b32_e32 v56, 16, v127
	v_and_b32_e32 v63, 0xffff0000, v129
	v_fmac_f32_e32 v62, v54, v56
	v_and_b32_e32 v54, 0xffff0000, v127
	v_mul_f32_e64 v51, v51, -v143
	v_fmac_f32_e32 v63, v55, v54
	v_add_f32_e32 v50, 1.0, v50
	v_mul_f32_e32 v51, 0x3fb8aa3b, v51
	v_mul_f32_e32 v54, v61, v61
	v_mul_f32_e32 v55, v63, v63
	v_rcp_f32_e32 v50, v50
	v_exp_f32_e32 v51, v51
	v_fmac_f32_e32 v54, v60, v60
	v_fmac_f32_e32 v55, v62, v62
	v_add_f32_e32 v54, v54, v55
	v_add_f32_e32 v54, v54, v59
	s_waitcnt vmcnt(29)
	v_lshlrev_b32_e32 v55, 16, v124
	s_waitcnt vmcnt(28)
	v_lshlrev_b32_e32 v59, 16, v122
	v_mul_f32_e64 v52, v52, -v143
	v_fmac_f32_e32 v55, v50, v59
	v_add_f32_e32 v50, 1.0, v51
	v_mul_f32_e32 v52, 0x3fb8aa3b, v52
	v_mul_f32_e64 v53, v53, -v143
	v_rcp_f32_e32 v50, v50
	v_exp_f32_e32 v52, v52
	v_mul_f32_e32 v53, 0x3fb8aa3b, v53
	v_exp_f32_e32 v53, v53
	v_and_b32_e32 v56, 0xffff0000, v124
	v_and_b32_e32 v51, 0xffff0000, v122
	v_fmac_f32_e32 v56, v50, v51
	v_add_f32_e32 v50, 1.0, v52
	v_rcp_f32_e32 v50, v50
	v_add_f32_e32 v51, 1.0, v53
	v_rcp_f32_e32 v51, v51
	v_lshlrev_b32_e32 v57, 16, v125
	v_lshlrev_b32_e32 v52, 16, v123
	v_and_b32_e32 v124, 0xffff0000, v125
	v_fmac_f32_e32 v57, v50, v52
	v_and_b32_e32 v50, 0xffff0000, v123
	v_fmac_f32_e32 v124, v51, v50
	v_mul_f32_e32 v50, v56, v56
	v_mul_f32_e32 v51, v124, v124
	v_fmac_f32_e32 v50, v55, v55
	v_fmac_f32_e32 v51, v57, v57
	v_add_f32_e32 v50, v50, v51
	v_add_f32_e32 v50, v50, v54
	ds_bpermute_b32 v51, v206, v50
	v_cvt_pk_bf16_f32 v59, v140, v141
	v_mov_b32_e32 v244, v58
	v_mov_b32_e32 v245, v59
	s_nop 1
	v_permlane16_swap_b32 v242, v244
	v_permlane16_swap_b32 v243, v245
	global_store_dwordx4 v[64:65], v[242:245], off
	v_cvt_pk_bf16_f32 v52, v60, v61
	v_cvt_pk_bf16_f32 v53, v62, v63
	s_waitcnt lgkmcnt(0)
	v_add_f32_e32 v50, v50, v51
	ds_bpermute_b32 v51, v207, v50
	v_mov_b32_e32 v242, v52
	v_mov_b32_e32 v243, v53
	v_cvt_pk_bf16_f32 v52, v55, v56
	v_cvt_pk_bf16_f32 v53, v57, v124
	v_mov_b32_e32 v244, v52
	v_mov_b32_e32 v245, v53
	s_nop 1
	v_permlane16_swap_b32 v242, v244
	v_permlane16_swap_b32 v243, v245
	global_store_dwordx4 v[64:65], v[242:245], off offset:256
	s_and_saveexec_b64 s[0:1], s[42:43]
	s_cbranch_execz .LBB0_55
	s_waitcnt lgkmcnt(0)
	v_add_f32_e32 v50, v50, v51
	global_atomic_add_f32 v[114:115], v50, off offset:512
; __device__ __forceinline__ unsigned cvt_pk_bf16(float lo, float hi) { unsigned r; asm volatile("v_cvt_pk_bf16_f32 %0, %1, %2" : "=v"(r) : "v"(lo), "v"(hi)); return r; }
;     __device__ __forceinline__ void operator()(const f32x4 (&acc)[2][2][4][2], const Unit& u, int wr, int wc, int fr, int fq) const {
;     ...
;             for (int m = 0; m < 4; ++m) { const int row = row0 + ai * HALF + m * 16; const size_t ro = (size_t)row * 2048 + col0;
;                 float sc = 1.f; if (GATE) sc = rsqrtf(scv[m] * (1.f / 2048.f) + 1e-6f);
;                 float s = 0.f;
; #pragma unroll
;                 for (int bj = 0; bj < 2; ++bj)
; #pragma unroll
;                     for (int n = 0; n < 2; ++n) { const size_t p = ro + bj * HALF + n * 16; const u32x2e hh = hw[m][bj][n], pp = pw[m][bj][n]; const f32x4 a = acc[ai][bj][m][n];
;                         f32x4 h; h[0] = __uint_as_float(hh.x << 16); h[1] = __uint_as_float(hh.x & 0xffff0000u); h[2] = __uint_as_float(hh.y << 16); h[3] = __uint_as_float(hh.y & 0xffff0000u);
;                         if (GATE) {
;                             h[0] += __builtin_amdgcn_rcpf(1.f + __expf(-sc * a[0])) * __uint_as_float(pp.x << 16); h[1] += __builtin_amdgcn_rcpf(1.f + __expf(-sc * a[1])) * __uint_as_float(pp.x & 0xffff0000u);
;                             h[2] += __builtin_amdgcn_rcpf(1.f + __expf(-sc * a[2])) * __uint_as_float(pp.y << 16); h[3] += __builtin_amdgcn_rcpf(1.f + __expf(-sc * a[3])) * __uint_as_float(pp.y & 0xffff0000u); }
;                         else h = h + a;
;                         s += (h[0] * h[0] + h[1] * h[1]) + (h[2] * h[2] + h[3] * h[3]);
;                         u32x2e o; o.x = cvt_pk_bf16(h[0], h[1]); o.y = cvt_pk_bf16(h[2], h[3]); *(u32x2e*)(Hout + p) = o; }
;                 s += __shfl_xor(s, 16); s += __shfl_xor(s, 32);
;                 if (fq == 0) atomicAdd(rss_out + row, s); }
.LBB0_55:
	s_or_b64 exec, exec, s[0:1]
	s_waitcnt vmcnt(17)
	v_fmamk_f32 v50, v142, 0x3a000000, v214
	s_waitcnt lgkmcnt(0)
	v_mul_f32_e32 v51, 0x4b800000, v50
	v_cmp_gt_f32_e32 vcc, s65, v50
	v_lshlrev_b32_e32 v53, 16, v118
	v_lshlrev_b32_e32 v57, 16, v116
	v_cndmask_b32_e32 v50, v50, v51, vcc
	v_rsq_f32_e32 v52, v50
	v_lshlrev_b32_e32 v55, 16, v119
	v_and_b32_e32 v56, 0xffff0000, v119
	v_lshlrev_b64 v[50:51], 12, v[120:121]
	v_mul_f32_e32 v54, 0x45800000, v52
	v_cndmask_b32_e32 v52, v52, v54, vcc
	v_mul_f32_e64 v46, v46, -v52
	v_mul_f32_e32 v46, 0x3fb8aa3b, v46
	v_exp_f32_e32 v46, v46
	v_mul_f32_e64 v47, v47, -v52
	v_mul_f32_e32 v47, 0x3fb8aa3b, v47
	v_exp_f32_e32 v47, v47
	v_add_f32_e32 v46, 1.0, v46
	v_rcp_f32_e32 v46, v46
	v_mul_f32_e64 v48, v48, -v52
	v_mul_f32_e32 v48, 0x3fb8aa3b, v48
	v_mul_f32_e64 v49, v49, -v52
	v_fmac_f32_e32 v53, v46, v57
	v_add_f32_e32 v46, 1.0, v47
	v_rcp_f32_e32 v46, v46
	v_exp_f32_e32 v48, v48
	v_mul_f32_e32 v49, 0x3fb8aa3b, v49
	v_exp_f32_e32 v49, v49
	v_and_b32_e32 v54, 0xffff0000, v118
	v_and_b32_e32 v47, 0xffff0000, v116
	v_fmac_f32_e32 v54, v46, v47
	v_add_f32_e32 v46, 1.0, v48
	v_mul_f32_e64 v42, v42, -v52
	v_rcp_f32_e32 v46, v46
	v_add_f32_e32 v47, 1.0, v49
	v_mul_f32_e32 v42, 0x3fb8aa3b, v42
	v_rcp_f32_e32 v47, v47
	v_exp_f32_e32 v42, v42
	v_lshlrev_b32_e32 v48, 16, v117
	v_fmac_f32_e32 v55, v46, v48
	v_and_b32_e32 v46, 0xffff0000, v117
	v_mul_f32_e64 v43, v43, -v52
	v_fmac_f32_e32 v56, v47, v46
	v_add_f32_e32 v42, 1.0, v42
	v_mul_f32_e32 v43, 0x3fb8aa3b, v43
	v_mul_f32_e32 v46, v54, v54
	v_mul_f32_e32 v47, v56, v56
	v_rcp_f32_e32 v42, v42
	v_exp_f32_e32 v43, v43
	v_fmac_f32_e32 v46, v53, v53
	v_fmac_f32_e32 v47, v55, v55
	v_lshl_add_u64 v[48:49], s[48:49], 0, v[50:51]
	v_add_f32_e32 v57, v46, v47
	v_cvt_pk_bf16_f32 v46, v53, v54
	v_lshl_add_u64 v[48:49], v[136:137], 1, v[48:49]
	v_cvt_pk_bf16_f32 v47, v55, v56
	v_add_u32_e32 v48, v250, v48
	v_mov_b32_e32 v242, v46
	v_mov_b32_e32 v243, v47
	v_lshlrev_b32_e32 v46, 16, v112
	v_lshlrev_b32_e32 v53, 16, v110
	v_mul_f32_e64 v44, v44, -v52
	v_fmac_f32_e32 v46, v42, v53
	v_add_f32_e32 v42, 1.0, v43
	v_mul_f32_e32 v44, 0x3fb8aa3b, v44
	v_mul_f32_e64 v38, v38, -v52
	v_rcp_f32_e32 v42, v42
	v_exp_f32_e32 v44, v44
	v_mul_f32_e32 v38, 0x3fb8aa3b, v38
	v_exp_f32_e32 v38, v38
	v_and_b32_e32 v47, 0xffff0000, v112
	v_and_b32_e32 v43, 0xffff0000, v110
	v_mul_f32_e64 v45, v45, -v52
	v_fmac_f32_e32 v47, v42, v43
	v_add_f32_e32 v42, 1.0, v44
	v_mul_f32_e64 v39, v39, -v52
	v_mul_f32_e32 v45, 0x3fb8aa3b, v45
	v_rcp_f32_e32 v42, v42
	v_add_f32_e32 v38, 1.0, v38
	v_mul_f32_e32 v39, 0x3fb8aa3b, v39
	v_exp_f32_e32 v45, v45
	v_rcp_f32_e32 v38, v38
	v_exp_f32_e32 v39, v39
	v_lshlrev_b32_e32 v50, 16, v113
	v_lshlrev_b32_e32 v44, 16, v111
	v_fmac_f32_e32 v50, v42, v44
	v_lshlrev_b32_e32 v44, 16, v108
	v_lshlrev_b32_e32 v53, 16, v106
	v_mul_f32_e64 v40, v40, -v52
	v_add_f32_e32 v43, 1.0, v45
	v_fmac_f32_e32 v44, v38, v53
	v_add_f32_e32 v38, 1.0, v39
	v_mul_f32_e32 v40, 0x3fb8aa3b, v40
	v_mul_f32_e64 v41, v41, -v52
	v_rcp_f32_e32 v43, v43
	v_rcp_f32_e32 v38, v38
	v_exp_f32_e32 v40, v40
	v_mul_f32_e32 v41, 0x3fb8aa3b, v41
	v_exp_f32_e32 v41, v41
	v_and_b32_e32 v51, 0xffff0000, v113
	v_and_b32_e32 v42, 0xffff0000, v111
	v_and_b32_e32 v45, 0xffff0000, v108
	v_and_b32_e32 v39, 0xffff0000, v106
	v_fmac_f32_e32 v51, v43, v42
	v_fmac_f32_e32 v45, v38, v39
	v_add_f32_e32 v38, 1.0, v40
	v_mul_f32_e64 v34, v34, -v52
	v_mul_f32_e32 v42, v47, v47
	v_mul_f32_e32 v43, v51, v51
	v_rcp_f32_e32 v38, v38
	v_add_f32_e32 v39, 1.0, v41
	v_mul_f32_e32 v34, 0x3fb8aa3b, v34
	v_fmac_f32_e32 v42, v46, v46
	v_fmac_f32_e32 v43, v50, v50
	v_rcp_f32_e32 v39, v39
	v_exp_f32_e32 v34, v34
	v_add_f32_e32 v42, v42, v43
	v_add_f32_e32 v43, v57, v42
	v_cvt_pk_bf16_f32 v42, v46, v47
	v_lshlrev_b32_e32 v46, 16, v109
	v_lshlrev_b32_e32 v40, 16, v107
	v_and_b32_e32 v47, 0xffff0000, v109
	v_fmac_f32_e32 v46, v38, v40
	v_and_b32_e32 v38, 0xffff0000, v107
	v_mul_f32_e64 v35, v35, -v52
	v_fmac_f32_e32 v47, v39, v38
	v_add_f32_e32 v34, 1.0, v34
	v_mul_f32_e32 v35, 0x3fb8aa3b, v35
	v_mul_f32_e32 v38, v45, v45
	v_mul_f32_e32 v39, v47, v47
	v_rcp_f32_e32 v34, v34
	v_exp_f32_e32 v35, v35
	v_fmac_f32_e32 v38, v44, v44
	v_fmac_f32_e32 v39, v46, v46
	v_add_f32_e32 v38, v38, v39
	v_add_f32_e32 v38, v38, v43
	v_lshlrev_b32_e32 v39, 16, v104
	v_lshlrev_b32_e32 v43, 16, v102
	v_mul_f32_e64 v36, v36, -v52
	v_fmac_f32_e32 v39, v34, v43
	v_add_f32_e32 v34, 1.0, v35
	v_mul_f32_e32 v36, 0x3fb8aa3b, v36
	v_mul_f32_e64 v37, v37, -v52
	v_rcp_f32_e32 v34, v34
	v_exp_f32_e32 v36, v36
	v_mul_f32_e32 v37, 0x3fb8aa3b, v37
	v_exp_f32_e32 v37, v37
	v_and_b32_e32 v40, 0xffff0000, v104
	v_and_b32_e32 v35, 0xffff0000, v102
	v_fmac_f32_e32 v40, v34, v35
	v_add_f32_e32 v34, 1.0, v36
	v_rcp_f32_e32 v34, v34
	v_add_f32_e32 v35, 1.0, v37
	v_rcp_f32_e32 v35, v35
	v_lshlrev_b32_e32 v41, 16, v105
	v_lshlrev_b32_e32 v36, 16, v103
	v_and_b32_e32 v53, 0xffff0000, v105
	v_fmac_f32_e32 v41, v34, v36
	v_and_b32_e32 v34, 0xffff0000, v103
	v_fmac_f32_e32 v53, v35, v34
	v_mul_f32_e32 v34, v40, v40
	v_mul_f32_e32 v35, v53, v53
	v_fmac_f32_e32 v34, v39, v39
	v_fmac_f32_e32 v35, v41, v41
	v_add_f32_e32 v34, v34, v35
	v_add_f32_e32 v34, v34, v38
	ds_bpermute_b32 v35, v206, v34
	v_cvt_pk_bf16_f32 v43, v50, v51
	v_mov_b32_e32 v244, v42
	v_mov_b32_e32 v245, v43
	s_nop 1
	v_permlane16_swap_b32 v242, v244
	v_permlane16_swap_b32 v243, v245
	global_store_dwordx4 v[48:49], v[242:245], off
	v_cvt_pk_bf16_f32 v36, v44, v45
	v_cvt_pk_bf16_f32 v37, v46, v47
	s_waitcnt lgkmcnt(0)
	v_add_f32_e32 v34, v34, v35
	ds_bpermute_b32 v35, v207, v34
	v_mov_b32_e32 v242, v36
	v_mov_b32_e32 v243, v37
	v_cvt_pk_bf16_f32 v36, v39, v40
	v_cvt_pk_bf16_f32 v37, v41, v53
	v_mov_b32_e32 v244, v36
	v_mov_b32_e32 v245, v37
	s_nop 1
	v_permlane16_swap_b32 v242, v244
	v_permlane16_swap_b32 v243, v245
	global_store_dwordx4 v[48:49], v[242:245], off offset:256
	s_and_saveexec_b64 s[0:1], s[42:43]
	s_cbranch_execz .LBB0_57
	s_waitcnt lgkmcnt(0)
	v_add_f32_e32 v34, v34, v35
	global_atomic_add_f32 v[114:115], v34, off offset:576
; __device__ __forceinline__ unsigned cvt_pk_bf16(float lo, float hi) { unsigned r; asm volatile("v_cvt_pk_bf16_f32 %0, %1, %2" : "=v"(r) : "v"(lo), "v"(hi)); return r; }
;     __device__ __forceinline__ void operator()(const f32x4 (&acc)[2][2][4][2], const Unit& u, int wr, int wc, int fr, int fq) const {
;     ...
;             for (int m = 0; m < 4; ++m) { const int row = row0 + ai * HALF + m * 16; const size_t ro = (size_t)row * 2048 + col0;
;                 float sc = 1.f; if (GATE) sc = rsqrtf(scv[m] * (1.f / 2048.f) + 1e-6f);
;                 float s = 0.f;
; #pragma unroll
;                 for (int bj = 0; bj < 2; ++bj)
; #pragma unroll
;                     for (int n = 0; n < 2; ++n) { const size_t p = ro + bj * HALF + n * 16; const u32x2e hh = hw[m][bj][n], pp = pw[m][bj][n]; const f32x4 a = acc[ai][bj][m][n];
;                         f32x4 h; h[0] = __uint_as_float(hh.x << 16); h[1] = __uint_as_float(hh.x & 0xffff0000u); h[2] = __uint_as_float(hh.y << 16); h[3] = __uint_as_float(hh.y & 0xffff0000u);
;                         if (GATE) {
;                             h[0] += __builtin_amdgcn_rcpf(1.f + __expf(-sc * a[0])) * __uint_as_float(pp.x << 16); h[1] += __builtin_amdgcn_rcpf(1.f + __expf(-sc * a[1])) * __uint_as_float(pp.x & 0xffff0000u);
;                             h[2] += __builtin_amdgcn_rcpf(1.f + __expf(-sc * a[2])) * __uint_as_float(pp.y << 16); h[3] += __builtin_amdgcn_rcpf(1.f + __expf(-sc * a[3])) * __uint_as_float(pp.y & 0xffff0000u); }
;                         else h = h + a;
;                         s += (h[0] * h[0] + h[1] * h[1]) + (h[2] * h[2] + h[3] * h[3]);
;                         u32x2e o; o.x = cvt_pk_bf16(h[0], h[1]); o.y = cvt_pk_bf16(h[2], h[3]); *(u32x2e*)(Hout + p) = o; }
;                 s += __shfl_xor(s, 16); s += __shfl_xor(s, 32);
;                 if (fq == 0) atomicAdd(rss_out + row, s); }
.LBB0_57:
	s_or_b64 exec, exec, s[0:1]
	s_waitcnt vmcnt(20)
	v_fmamk_f32 v34, v139, 0x3a000000, v214
	s_waitcnt lgkmcnt(0)
	v_mul_f32_e32 v35, 0x4b800000, v34
	v_cmp_gt_f32_e32 vcc, s65, v34
	v_lshlrev_b32_e32 v37, 16, v98
	v_lshlrev_b32_e32 v41, 16, v96
	v_cndmask_b32_e32 v34, v34, v35, vcc
	v_rsq_f32_e32 v36, v34
	v_lshlrev_b32_e32 v39, 16, v99
	v_and_b32_e32 v40, 0xffff0000, v99
	v_lshlrev_b64 v[34:35], 12, v[100:101]
	v_mul_f32_e32 v38, 0x45800000, v36
	v_cndmask_b32_e32 v36, v36, v38, vcc
	v_mul_f32_e64 v30, v30, -v36
	v_mul_f32_e32 v30, 0x3fb8aa3b, v30
	v_exp_f32_e32 v30, v30
	v_mul_f32_e64 v31, v31, -v36
	v_mul_f32_e32 v31, 0x3fb8aa3b, v31
	v_exp_f32_e32 v31, v31
	v_add_f32_e32 v30, 1.0, v30
	v_rcp_f32_e32 v30, v30
	v_mul_f32_e64 v32, v32, -v36
	v_mul_f32_e32 v32, 0x3fb8aa3b, v32
	v_mul_f32_e64 v33, v33, -v36
	v_fmac_f32_e32 v37, v30, v41
	v_add_f32_e32 v30, 1.0, v31
	v_rcp_f32_e32 v30, v30
	v_exp_f32_e32 v32, v32
	v_mul_f32_e32 v33, 0x3fb8aa3b, v33
	v_exp_f32_e32 v33, v33
	v_and_b32_e32 v38, 0xffff0000, v98
	v_and_b32_e32 v31, 0xffff0000, v96
	v_fmac_f32_e32 v38, v30, v31
	v_add_f32_e32 v30, 1.0, v32
	v_mul_f32_e64 v26, v26, -v36
	v_rcp_f32_e32 v30, v30
	v_add_f32_e32 v31, 1.0, v33
	v_mul_f32_e32 v26, 0x3fb8aa3b, v26
	v_rcp_f32_e32 v31, v31
	v_exp_f32_e32 v26, v26
	v_lshlrev_b32_e32 v32, 16, v97
	v_fmac_f32_e32 v39, v30, v32
	v_and_b32_e32 v30, 0xffff0000, v97
	v_mul_f32_e64 v27, v27, -v36
	v_fmac_f32_e32 v40, v31, v30
	v_add_f32_e32 v26, 1.0, v26
	v_mul_f32_e32 v27, 0x3fb8aa3b, v27
	v_mul_f32_e32 v30, v38, v38
	v_mul_f32_e32 v31, v40, v40
	v_rcp_f32_e32 v26, v26
	v_exp_f32_e32 v27, v27
	v_fmac_f32_e32 v30, v37, v37
	v_fmac_f32_e32 v31, v39, v39
	v_lshl_add_u64 v[32:33], s[48:49], 0, v[34:35]
	v_add_f32_e32 v41, v30, v31
	v_cvt_pk_bf16_f32 v30, v37, v38
	v_lshl_add_u64 v[32:33], v[136:137], 1, v[32:33]
	v_cvt_pk_bf16_f32 v31, v39, v40
	v_add_u32_e32 v32, v250, v32
	v_mov_b32_e32 v242, v30
	v_mov_b32_e32 v243, v31
	v_lshlrev_b32_e32 v30, 16, v94
	v_lshlrev_b32_e32 v37, 16, v92
	v_mul_f32_e64 v28, v28, -v36
	v_fmac_f32_e32 v30, v26, v37
	v_add_f32_e32 v26, 1.0, v27
	v_mul_f32_e32 v28, 0x3fb8aa3b, v28
	v_mul_f32_e64 v22, v22, -v36
	v_rcp_f32_e32 v26, v26
	v_exp_f32_e32 v28, v28
	v_mul_f32_e32 v22, 0x3fb8aa3b, v22
	v_exp_f32_e32 v22, v22
	v_and_b32_e32 v31, 0xffff0000, v94
	v_and_b32_e32 v27, 0xffff0000, v92
	v_mul_f32_e64 v29, v29, -v36
	v_fmac_f32_e32 v31, v26, v27
	v_add_f32_e32 v26, 1.0, v28
	v_mul_f32_e64 v23, v23, -v36
	v_mul_f32_e32 v29, 0x3fb8aa3b, v29
	v_rcp_f32_e32 v26, v26
	v_add_f32_e32 v22, 1.0, v22
	v_mul_f32_e32 v23, 0x3fb8aa3b, v23
	v_exp_f32_e32 v29, v29
	v_rcp_f32_e32 v22, v22
	v_exp_f32_e32 v23, v23
	v_lshlrev_b32_e32 v34, 16, v95
	v_lshlrev_b32_e32 v28, 16, v93
	v_fmac_f32_e32 v34, v26, v28
	v_lshlrev_b32_e32 v28, 16, v90
	s_waitcnt vmcnt(19)
	v_lshlrev_b32_e32 v37, 16, v88
	v_mul_f32_e64 v24, v24, -v36
	v_add_f32_e32 v27, 1.0, v29
	v_fmac_f32_e32 v28, v22, v37
	v_add_f32_e32 v22, 1.0, v23
	v_mul_f32_e32 v24, 0x3fb8aa3b, v24
	v_mul_f32_e64 v25, v25, -v36
	v_rcp_f32_e32 v27, v27
	v_rcp_f32_e32 v22, v22
	v_exp_f32_e32 v24, v24
	v_mul_f32_e32 v25, 0x3fb8aa3b, v25
	v_exp_f32_e32 v25, v25
	v_and_b32_e32 v35, 0xffff0000, v95
	v_and_b32_e32 v26, 0xffff0000, v93
	v_and_b32_e32 v29, 0xffff0000, v90
	v_and_b32_e32 v23, 0xffff0000, v88
	v_fmac_f32_e32 v35, v27, v26
	v_fmac_f32_e32 v29, v22, v23
	v_add_f32_e32 v22, 1.0, v24
	v_mul_f32_e64 v18, v18, -v36
	v_mul_f32_e32 v26, v31, v31
	v_mul_f32_e32 v27, v35, v35
	v_rcp_f32_e32 v22, v22
	v_add_f32_e32 v23, 1.0, v25
	v_mul_f32_e32 v18, 0x3fb8aa3b, v18
	v_fmac_f32_e32 v26, v30, v30
	v_fmac_f32_e32 v27, v34, v34
	v_rcp_f32_e32 v23, v23
	v_exp_f32_e32 v18, v18
	v_add_f32_e32 v26, v26, v27
	v_add_f32_e32 v27, v41, v26
	v_cvt_pk_bf16_f32 v26, v30, v31
	v_lshlrev_b32_e32 v30, 16, v91
	v_lshlrev_b32_e32 v24, 16, v89
	v_and_b32_e32 v31, 0xffff0000, v91
	v_fmac_f32_e32 v30, v22, v24
	v_and_b32_e32 v22, 0xffff0000, v89
	v_mul_f32_e64 v19, v19, -v36
	v_fmac_f32_e32 v31, v23, v22
	v_add_f32_e32 v18, 1.0, v18
	v_mul_f32_e32 v19, 0x3fb8aa3b, v19
	v_mul_f32_e32 v22, v29, v29
	v_mul_f32_e32 v23, v31, v31
	v_rcp_f32_e32 v18, v18
	v_exp_f32_e32 v19, v19
	v_fmac_f32_e32 v22, v28, v28
	v_fmac_f32_e32 v23, v30, v30
	v_add_f32_e32 v22, v22, v23
	v_add_f32_e32 v22, v22, v27
	s_waitcnt vmcnt(18)
	v_lshlrev_b32_e32 v23, 16, v86
	s_waitcnt vmcnt(17)
	v_lshlrev_b32_e32 v27, 16, v84
	v_mul_f32_e64 v20, v20, -v36
	v_fmac_f32_e32 v23, v18, v27
	v_add_f32_e32 v18, 1.0, v19
	v_mul_f32_e32 v20, 0x3fb8aa3b, v20
	v_mul_f32_e64 v21, v21, -v36
	v_rcp_f32_e32 v18, v18
	v_exp_f32_e32 v20, v20
	v_mul_f32_e32 v21, 0x3fb8aa3b, v21
	v_exp_f32_e32 v21, v21
	v_and_b32_e32 v24, 0xffff0000, v86
	v_and_b32_e32 v19, 0xffff0000, v84
	v_fmac_f32_e32 v24, v18, v19
	v_add_f32_e32 v18, 1.0, v20
	v_rcp_f32_e32 v18, v18
	v_add_f32_e32 v19, 1.0, v21
	v_rcp_f32_e32 v19, v19
	v_lshlrev_b32_e32 v25, 16, v87
	v_lshlrev_b32_e32 v20, 16, v85
	v_and_b32_e32 v37, 0xffff0000, v87
	v_fmac_f32_e32 v25, v18, v20
	v_and_b32_e32 v18, 0xffff0000, v85
	v_fmac_f32_e32 v37, v19, v18
	v_mul_f32_e32 v18, v24, v24
	v_mul_f32_e32 v19, v37, v37
	v_fmac_f32_e32 v18, v23, v23
	v_fmac_f32_e32 v19, v25, v25
	v_add_f32_e32 v18, v18, v19
	v_add_f32_e32 v18, v18, v22
	ds_bpermute_b32 v19, v206, v18
	v_cvt_pk_bf16_f32 v27, v34, v35
	v_mov_b32_e32 v244, v26
	v_mov_b32_e32 v245, v27
	s_nop 1
	v_permlane16_swap_b32 v242, v244
	v_permlane16_swap_b32 v243, v245
	global_store_dwordx4 v[32:33], v[242:245], off
	v_cvt_pk_bf16_f32 v20, v28, v29
	v_cvt_pk_bf16_f32 v21, v30, v31
	s_waitcnt lgkmcnt(0)
	v_add_f32_e32 v18, v18, v19
	ds_bpermute_b32 v19, v207, v18
	v_mov_b32_e32 v242, v20
	v_mov_b32_e32 v243, v21
	v_cvt_pk_bf16_f32 v20, v23, v24
	v_cvt_pk_bf16_f32 v21, v25, v37
	v_mov_b32_e32 v244, v20
	v_mov_b32_e32 v245, v21
	s_nop 1
	v_permlane16_swap_b32 v242, v244
	v_permlane16_swap_b32 v243, v245
	global_store_dwordx4 v[32:33], v[242:245], off offset:256
	s_and_saveexec_b64 s[0:1], s[42:43]
	s_cbranch_execz .LBB0_59
	s_waitcnt lgkmcnt(0)
	v_add_f32_e32 v18, v18, v19
	global_atomic_add_f32 v[114:115], v18, off offset:640
; __device__ __forceinline__ unsigned cvt_pk_bf16(float lo, float hi) { unsigned r; asm volatile("v_cvt_pk_bf16_f32 %0, %1, %2" : "=v"(r) : "v"(lo), "v"(hi)); return r; }
;     __device__ __forceinline__ void operator()(const f32x4 (&acc)[2][2][4][2], const Unit& u, int wr, int wc, int fr, int fq) const {
;     ...
;             for (int m = 0; m < 4; ++m) { const int row = row0 + ai * HALF + m * 16; const size_t ro = (size_t)row * 2048 + col0;
;                 float sc = 1.f; if (GATE) sc = rsqrtf(scv[m] * (1.f / 2048.f) + 1e-6f);
;                 float s = 0.f;
; #pragma unroll
;                 for (int bj = 0; bj < 2; ++bj)
; #pragma unroll
;                     for (int n = 0; n < 2; ++n) { const size_t p = ro + bj * HALF + n * 16; const u32x2e hh = hw[m][bj][n], pp = pw[m][bj][n]; const f32x4 a = acc[ai][bj][m][n];
;                         f32x4 h; h[0] = __uint_as_float(hh.x << 16); h[1] = __uint_as_float(hh.x & 0xffff0000u); h[2] = __uint_as_float(hh.y << 16); h[3] = __uint_as_float(hh.y & 0xffff0000u);
;                         if (GATE) {
;                             h[0] += __builtin_amdgcn_rcpf(1.f + __expf(-sc * a[0])) * __uint_as_float(pp.x << 16); h[1] += __builtin_amdgcn_rcpf(1.f + __expf(-sc * a[1])) * __uint_as_float(pp.x & 0xffff0000u);
;                             h[2] += __builtin_amdgcn_rcpf(1.f + __expf(-sc * a[2])) * __uint_as_float(pp.y << 16); h[3] += __builtin_amdgcn_rcpf(1.f + __expf(-sc * a[3])) * __uint_as_float(pp.y & 0xffff0000u); }
;                         else h = h + a;
;                         s += (h[0] * h[0] + h[1] * h[1]) + (h[2] * h[2] + h[3] * h[3]);
;                         u32x2e o; o.x = cvt_pk_bf16(h[0], h[1]); o.y = cvt_pk_bf16(h[2], h[3]); *(u32x2e*)(Hout + p) = o; }
;                 s += __shfl_xor(s, 16); s += __shfl_xor(s, 32);
;                 if (fq == 0) atomicAdd(rss_out + row, s); }
.LBB0_59:
	s_or_b64 exec, exec, s[0:1]
	v_fmamk_f32 v18, v138, 0x3a000000, v214
	s_waitcnt lgkmcnt(0)
	v_mul_f32_e32 v19, 0x4b800000, v18
	v_cmp_gt_f32_e32 vcc, s65, v18
	s_waitcnt vmcnt(19)
	v_lshlrev_b32_e32 v21, 16, v80
	s_waitcnt vmcnt(18)
	v_lshlrev_b32_e32 v25, 16, v78
	v_cndmask_b32_e32 v18, v18, v19, vcc
	v_rsq_f32_e32 v20, v18
	v_lshlrev_b32_e32 v23, 16, v81
	v_and_b32_e32 v24, 0xffff0000, v81
	v_lshlrev_b64 v[18:19], 12, v[82:83]
	v_mul_f32_e32 v22, 0x45800000, v20
	v_cndmask_b32_e32 v20, v20, v22, vcc
	v_mul_f32_e64 v14, v14, -v20
	v_mul_f32_e32 v14, 0x3fb8aa3b, v14
	v_exp_f32_e32 v14, v14
	v_mul_f32_e64 v15, v15, -v20
	v_mul_f32_e32 v15, 0x3fb8aa3b, v15
	v_exp_f32_e32 v15, v15
	v_add_f32_e32 v14, 1.0, v14
	v_rcp_f32_e32 v14, v14
	v_mul_f32_e64 v16, v16, -v20
	v_mul_f32_e32 v16, 0x3fb8aa3b, v16
	v_mul_f32_e64 v17, v17, -v20
	v_fmac_f32_e32 v21, v14, v25
	v_add_f32_e32 v14, 1.0, v15
	v_rcp_f32_e32 v14, v14
	v_exp_f32_e32 v16, v16
	v_mul_f32_e32 v17, 0x3fb8aa3b, v17
	v_exp_f32_e32 v17, v17
	v_and_b32_e32 v22, 0xffff0000, v80
	v_and_b32_e32 v15, 0xffff0000, v78
	v_fmac_f32_e32 v22, v14, v15
	v_add_f32_e32 v14, 1.0, v16
	v_mul_f32_e64 v10, v10, -v20
	v_rcp_f32_e32 v14, v14
	v_add_f32_e32 v15, 1.0, v17
	v_mul_f32_e32 v10, 0x3fb8aa3b, v10
	v_rcp_f32_e32 v15, v15
	v_exp_f32_e32 v10, v10
	v_lshlrev_b32_e32 v16, 16, v79
	v_fmac_f32_e32 v23, v14, v16
	v_and_b32_e32 v14, 0xffff0000, v79
	v_mul_f32_e64 v11, v11, -v20
	v_fmac_f32_e32 v24, v15, v14
	v_add_f32_e32 v10, 1.0, v10
	v_mul_f32_e32 v11, 0x3fb8aa3b, v11
	v_mul_f32_e32 v14, v22, v22
	v_mul_f32_e32 v15, v24, v24
	v_rcp_f32_e32 v10, v10
	v_exp_f32_e32 v11, v11
	v_fmac_f32_e32 v14, v21, v21
	v_fmac_f32_e32 v15, v23, v23
	v_lshl_add_u64 v[16:17], s[48:49], 0, v[18:19]
	v_add_f32_e32 v25, v14, v15
	v_cvt_pk_bf16_f32 v14, v21, v22
	v_lshl_add_u64 v[16:17], v[136:137], 1, v[16:17]
	v_cvt_pk_bf16_f32 v15, v23, v24
	v_add_u32_e32 v16, v250, v16
	v_mov_b32_e32 v242, v14
	v_mov_b32_e32 v243, v15
	s_waitcnt vmcnt(18)
	v_lshlrev_b32_e32 v14, 16, v76
	s_waitcnt vmcnt(17)
	v_lshlrev_b32_e32 v21, 16, v74
	v_mul_f32_e64 v12, v12, -v20
	v_fmac_f32_e32 v14, v10, v21
	v_add_f32_e32 v10, 1.0, v11
	v_mul_f32_e32 v12, 0x3fb8aa3b, v12
	v_mul_f32_e64 v6, v6, -v20
	v_rcp_f32_e32 v10, v10
	v_exp_f32_e32 v12, v12
	v_mul_f32_e32 v6, 0x3fb8aa3b, v6
	v_exp_f32_e32 v6, v6
	v_and_b32_e32 v15, 0xffff0000, v76
	v_and_b32_e32 v11, 0xffff0000, v74
	v_mul_f32_e64 v13, v13, -v20
	v_fmac_f32_e32 v15, v10, v11
	v_add_f32_e32 v10, 1.0, v12
	v_mul_f32_e64 v7, v7, -v20
	v_mul_f32_e32 v13, 0x3fb8aa3b, v13
	v_rcp_f32_e32 v10, v10
	v_add_f32_e32 v6, 1.0, v6
	v_mul_f32_e32 v7, 0x3fb8aa3b, v7
	v_exp_f32_e32 v13, v13
	v_rcp_f32_e32 v6, v6
	v_exp_f32_e32 v7, v7
	v_lshlrev_b32_e32 v18, 16, v77
	v_lshlrev_b32_e32 v12, 16, v75
	v_fmac_f32_e32 v18, v10, v12
	s_waitcnt vmcnt(16)
	v_lshlrev_b32_e32 v12, 16, v72
	s_waitcnt vmcnt(15)
	v_lshlrev_b32_e32 v21, 16, v70
	v_mul_f32_e64 v8, v8, -v20
	v_add_f32_e32 v11, 1.0, v13
	v_fmac_f32_e32 v12, v6, v21
	v_add_f32_e32 v6, 1.0, v7
	v_mul_f32_e32 v8, 0x3fb8aa3b, v8
	v_mul_f32_e64 v9, v9, -v20
	v_rcp_f32_e32 v11, v11
	v_rcp_f32_e32 v6, v6
	v_exp_f32_e32 v8, v8
	v_mul_f32_e32 v9, 0x3fb8aa3b, v9
	v_exp_f32_e32 v9, v9
	v_and_b32_e32 v19, 0xffff0000, v77
	v_and_b32_e32 v10, 0xffff0000, v75
	v_and_b32_e32 v13, 0xffff0000, v72
	v_and_b32_e32 v7, 0xffff0000, v70
	v_fmac_f32_e32 v19, v11, v10
	v_fmac_f32_e32 v13, v6, v7
	v_add_f32_e32 v6, 1.0, v8
	v_mul_f32_e64 v2, v2, -v20
	v_mul_f32_e32 v10, v15, v15
	v_mul_f32_e32 v11, v19, v19
	v_rcp_f32_e32 v6, v6
	v_add_f32_e32 v7, 1.0, v9
	v_mul_f32_e32 v2, 0x3fb8aa3b, v2
	v_fmac_f32_e32 v10, v14, v14
	v_fmac_f32_e32 v11, v18, v18
	v_rcp_f32_e32 v7, v7
	v_exp_f32_e32 v2, v2
	v_add_f32_e32 v10, v10, v11
	v_add_f32_e32 v11, v25, v10
	v_cvt_pk_bf16_f32 v10, v14, v15
	v_lshlrev_b32_e32 v14, 16, v73
	v_lshlrev_b32_e32 v8, 16, v71
	v_and_b32_e32 v15, 0xffff0000, v73
	v_fmac_f32_e32 v14, v6, v8
	v_and_b32_e32 v6, 0xffff0000, v71
	v_mul_f32_e64 v3, v3, -v20
	v_fmac_f32_e32 v15, v7, v6
	v_add_f32_e32 v2, 1.0, v2
	v_mul_f32_e32 v3, 0x3fb8aa3b, v3
	v_mul_f32_e32 v6, v13, v13
	v_mul_f32_e32 v7, v15, v15
	v_rcp_f32_e32 v2, v2
	v_exp_f32_e32 v3, v3
	v_fmac_f32_e32 v6, v12, v12
	v_fmac_f32_e32 v7, v14, v14
	v_add_f32_e32 v6, v6, v7
	v_add_f32_e32 v6, v6, v11
	s_waitcnt vmcnt(14)
	v_lshlrev_b32_e32 v7, 16, v68
	s_waitcnt vmcnt(13)
	v_lshlrev_b32_e32 v11, 16, v66
	v_mul_f32_e64 v4, v4, -v20
	v_fmac_f32_e32 v7, v2, v11
	v_add_f32_e32 v2, 1.0, v3
	v_mul_f32_e32 v4, 0x3fb8aa3b, v4
	v_mul_f32_e64 v5, v5, -v20
	v_rcp_f32_e32 v2, v2
	v_exp_f32_e32 v4, v4
	v_mul_f32_e32 v5, 0x3fb8aa3b, v5
	v_exp_f32_e32 v5, v5
	v_and_b32_e32 v8, 0xffff0000, v68
	v_and_b32_e32 v3, 0xffff0000, v66
	v_fmac_f32_e32 v8, v2, v3
	v_add_f32_e32 v2, 1.0, v4
	v_rcp_f32_e32 v2, v2
	v_add_f32_e32 v3, 1.0, v5
	v_rcp_f32_e32 v3, v3
	v_lshlrev_b32_e32 v9, 16, v69
	v_lshlrev_b32_e32 v4, 16, v67
	v_and_b32_e32 v21, 0xffff0000, v69
	v_fmac_f32_e32 v9, v2, v4
	v_and_b32_e32 v2, 0xffff0000, v67
	v_fmac_f32_e32 v21, v3, v2
	v_mul_f32_e32 v2, v8, v8
	v_mul_f32_e32 v3, v21, v21
	v_fmac_f32_e32 v2, v7, v7
	v_fmac_f32_e32 v3, v9, v9
	v_add_f32_e32 v2, v2, v3
	v_add_f32_e32 v2, v2, v6
	ds_bpermute_b32 v3, v206, v2
	v_cvt_pk_bf16_f32 v11, v18, v19
	v_mov_b32_e32 v244, v10
	v_mov_b32_e32 v245, v11
	s_nop 1
	v_permlane16_swap_b32 v242, v244
	v_permlane16_swap_b32 v243, v245
	global_store_dwordx4 v[16:17], v[242:245], off
	v_cvt_pk_bf16_f32 v4, v12, v13
	v_cvt_pk_bf16_f32 v5, v14, v15
	s_waitcnt lgkmcnt(0)
	v_add_f32_e32 v2, v2, v3
	ds_bpermute_b32 v3, v207, v2
	v_mov_b32_e32 v242, v4
	v_mov_b32_e32 v243, v5
	v_cvt_pk_bf16_f32 v4, v7, v8
	v_cvt_pk_bf16_f32 v5, v9, v21
	v_mov_b32_e32 v244, v4
	v_mov_b32_e32 v245, v5
	s_nop 1
	v_permlane16_swap_b32 v242, v244
	v_permlane16_swap_b32 v243, v245
	global_store_dwordx4 v[16:17], v[242:245], off offset:256
	s_and_saveexec_b64 s[0:1], s[42:43]
	s_cbranch_execz .LBB0_36
	s_waitcnt lgkmcnt(0)
	v_add_f32_e32 v2, v2, v3
	global_atomic_add_f32 v[114:115], v2, off offset:704
	s_branch .LBB0_36

;     __device__ __forceinline__ void operator()(const f32x4 (&acc)[2][2][4][2], const Unit& u, int wr, int wc, int fr, int fq) const {
;         const int row0 = u.pm * BM + wr * 64 + fr, col0 = u.pn * BM + wc * 32 + 4 * fq;
; #pragma unroll
;         for (int ai = 0; ai < 2; ++ai) {
;             u32x2e hw[4][2][2], pw[4][2][2]; float scv[4];
; #pragma unroll
;             for (int m = 0; m < 4; ++m) { const int row = row0 + ai * HALF + m * 16; const size_t ro = (size_t)row * 2048 + col0;
;                 scv[m] = GATE ? rss_in[row] : 0.f;
; #pragma unroll
;                 for (int bj = 0; bj < 2; ++bj)
; #pragma unroll
;                     for (int n = 0; n < 2; ++n) { const size_t p = ro + bj * HALF + n * 16; hw[m][bj][n] = *(const u32x2e*)(Hin + p); if (GATE) pw[m][bj][n] = *(const u32x2e*)(PP + p); else pw[m][bj][n] = (u32x2e){0u, 0u}; } }
.Lepi2_noalign:
	s_waitcnt vmcnt(0)
	s_barrier
	v_lshlrev_b32_e32 v130, 9, v174
	v_lshrrev_b32_e32 v131, 3, v176
	v_and_b32_e32 v132, 15, v174
	v_xor_b32_e32 v131, v131, v132
	v_lshl_add_u32 v130, v131, 4, v130
	v_bfe_u32 v131, v176, 2, 1
	v_lshl_add_u32 v130, v131, 3, v130
	v_xor_b32_e32 v131, 32, v130
	v_add_u32_e32 v132, 0x10000, v130
	v_add_u32_e32 v133, 0x10000, v131
	v_lshrrev_b32_e32 v134, 5, v216
	v_and_b32_e32 v135, 31, v216
	v_xor_b32_e32 v135, v135, v134
	v_lshlrev_b32_e32 v135, 4, v135
	v_lshl_or_b32 v134, v134, 12, v135
	v_lshrrev_b32_e32 v135, 6, v183
	s_nop 0
	v_readfirstlane_b32 s7, v135
	s_lshl_b32 s8, s4, 20
	s_lshl_b32 s9, s6, 9
	s_add_i32 s8, s8, s9
	s_lshl_b32 s9, s7, 16
	s_add_i32 s8, s8, s9
	s_lshl_b32 s7, s7, 13
	s_add_u32 s10, s46, s8
	s_addc_u32 s11, s47, 0
	s_add_i32 m0, s7, 0x0
	s_add_u32 s2, s10, 0x0
	s_addc_u32 s3, s11, 0
	v_xor_b32_e32 v135, 0x0, v134
	global_load_lds_dwordx4 v135, s[2:3]
	s_add_i32 m0, s7, 0x400
	s_add_u32 s2, s10, 0x2000
	s_addc_u32 s3, s11, 0
	v_xor_b32_e32 v135, 0x20, v134
	global_load_lds_dwordx4 v135, s[2:3]
	s_add_i32 m0, s7, 0x800
	s_add_u32 s2, s10, 0x4000
	s_addc_u32 s3, s11, 0
	v_xor_b32_e32 v135, 0x40, v134
	global_load_lds_dwordx4 v135, s[2:3]
	s_add_i32 m0, s7, 0xc00
	s_add_u32 s2, s10, 0x6000
	s_addc_u32 s3, s11, 0
	v_xor_b32_e32 v135, 0x60, v134
	global_load_lds_dwordx4 v135, s[2:3]
	s_add_i32 m0, s7, 0x1000
	s_add_u32 s2, s10, 0x8000
	s_addc_u32 s3, s11, 0
	v_xor_b32_e32 v135, 0x80, v134
	global_load_lds_dwordx4 v135, s[2:3]
	s_add_i32 m0, s7, 0x1400
	s_add_u32 s2, s10, 0xa000
	s_addc_u32 s3, s11, 0
	v_xor_b32_e32 v135, 0xa0, v134
	global_load_lds_dwordx4 v135, s[2:3]
	s_add_i32 m0, s7, 0x1800
	s_add_u32 s2, s10, 0xc000
	s_addc_u32 s3, s11, 0
	v_xor_b32_e32 v135, 0xc0, v134
	global_load_lds_dwordx4 v135, s[2:3]
	s_add_i32 m0, s7, 0x1c00
	s_add_u32 s2, s10, 0xe000
	s_addc_u32 s3, s11, 0
	v_xor_b32_e32 v135, 0xe0, v134
	global_load_lds_dwordx4 v135, s[2:3]
	s_waitcnt vmcnt(0)
	s_barrier
	v_lshl_or_b32 v136, s6, 8, v176
	v_lshl_add_u32 v170, s4, 8, v174
	v_ashrrev_i32_e32 v137, 31, v136
	v_lshlrev_b64 v[178:179], 1, v[136:137]
	v_ashrrev_i32_e32 v171, 31, v170
	v_lshl_add_u64 v[138:139], s[46:47], 0, v[178:179]
	v_lshlrev_b64 v[140:141], 12, v[170:171]
	v_lshl_add_u64 v[142:143], v[138:139], 0, v[140:141]
	ds_read_b64 v[180:181], v130 offset:0
	ds_read_b64 v[192:193], v131 offset:0
	ds_read_b64 v[194:195], v130 offset:256
	ds_read_b64 v[196:197], v131 offset:256
	v_or_b32_e32 v142, 16, v170
	v_ashrrev_i32_e32 v143, 31, v142
	v_lshlrev_b64 v[168:169], 12, v[142:143]
	v_lshl_add_u64 v[142:143], v[138:139], 0, v[168:169]
	ds_read_b64 v[172:173], v130 offset:8192
	ds_read_b64 v[166:167], v131 offset:8192
	ds_read_b64 v[164:165], v130 offset:8448
	ds_read_b64 v[162:163], v131 offset:8448
	v_or_b32_e32 v142, 32, v170
	v_ashrrev_i32_e32 v143, 31, v142
	v_lshlrev_b64 v[158:159], 12, v[142:143]
	v_lshl_add_u64 v[142:143], v[138:139], 0, v[158:159]
	ds_read_b64 v[160:161], v130 offset:16384
	ds_read_b64 v[156:157], v131 offset:16384
	ds_read_b64 v[152:153], v130 offset:16640
	ds_read_b64 v[148:149], v131 offset:16640
	v_or_b32_e32 v142, 48, v170
	v_ashrrev_i32_e32 v143, 31, v142
	v_lshlrev_b64 v[144:145], 12, v[142:143]
	v_lshl_add_u64 v[142:143], v[138:139], 0, v[144:145]
	ds_read_b64 v[154:155], v130 offset:24576
	ds_read_b64 v[150:151], v131 offset:24576
	ds_read_b64 v[146:147], v130 offset:24832
	s_nop 0
	ds_read_b64 v[142:143], v131 offset:24832
	s_waitcnt vmcnt(0) lgkmcnt(0)
	s_barrier
	s_add_i32 m0, s7, 0x0
	s_add_u32 s2, s10, 0x80000
	s_addc_u32 s3, s11, 0
	v_xor_b32_e32 v135, 0x0, v134
	global_load_lds_dwordx4 v135, s[2:3]
	s_add_i32 m0, s7, 0x400
	s_add_u32 s2, s10, 0x82000
	s_addc_u32 s3, s11, 0
	v_xor_b32_e32 v135, 0x20, v134
	global_load_lds_dwordx4 v135, s[2:3]
	s_add_i32 m0, s7, 0x800
	s_add_u32 s2, s10, 0x84000
	s_addc_u32 s3, s11, 0
	v_xor_b32_e32 v135, 0x40, v134
	global_load_lds_dwordx4 v135, s[2:3]
	s_add_i32 m0, s7, 0xc00
	s_add_u32 s2, s10, 0x86000
	s_addc_u32 s3, s11, 0
	v_xor_b32_e32 v135, 0x60, v134
	global_load_lds_dwordx4 v135, s[2:3]
	s_add_i32 m0, s7, 0x1000
	s_add_u32 s2, s10, 0x88000
	s_addc_u32 s3, s11, 0
	v_xor_b32_e32 v135, 0x80, v134
	global_load_lds_dwordx4 v135, s[2:3]
	s_add_i32 m0, s7, 0x1400
	s_add_u32 s2, s10, 0x8a000
	s_addc_u32 s3, s11, 0
	v_xor_b32_e32 v135, 0xa0, v134
	global_load_lds_dwordx4 v135, s[2:3]
	s_add_i32 m0, s7, 0x1800
	s_add_u32 s2, s10, 0x8c000
	s_addc_u32 s3, s11, 0
	v_xor_b32_e32 v135, 0xc0, v134
	global_load_lds_dwordx4 v135, s[2:3]
	s_add_i32 m0, s7, 0x1c00
	s_add_u32 s2, s10, 0x8e000
	s_addc_u32 s3, s11, 0
	v_xor_b32_e32 v135, 0xe0, v134
	global_load_lds_dwordx4 v135, s[2:3]
	s_waitcnt vmcnt(0)
; __device__ __forceinline__ unsigned cvt_pk_bf16(float lo, float hi) { unsigned r; asm volatile("v_cvt_pk_bf16_f32 %0, %1, %2" : "=v"(r) : "v"(lo), "v"(hi)); return r; }
;     __device__ __forceinline__ void operator()(const f32x4 (&acc)[2][2][4][2], const Unit& u, int wr, int wc, int fr, int fq) const {
;     ...
;             for (int m = 0; m < 4; ++m) { const int row = row0 + ai * HALF + m * 16; const size_t ro = (size_t)row * 2048 + col0;
;                 float sc = 1.f; if (GATE) sc = rsqrtf(scv[m] * (1.f / 2048.f) + 1e-6f);
;                 float s = 0.f;
; #pragma unroll
;                 for (int bj = 0; bj < 2; ++bj)
; #pragma unroll
;                     for (int n = 0; n < 2; ++n) { const size_t p = ro + bj * HALF + n * 16; const u32x2e hh = hw[m][bj][n], pp = pw[m][bj][n]; const f32x4 a = acc[ai][bj][m][n];
;                         f32x4 h; h[0] = __uint_as_float(hh.x << 16); h[1] = __uint_as_float(hh.x & 0xffff0000u); h[2] = __uint_as_float(hh.y << 16); h[3] = __uint_as_float(hh.y & 0xffff0000u);
;                         if (GATE) {
;                             h[0] += __builtin_amdgcn_rcpf(1.f + __expf(-sc * a[0])) * __uint_as_float(pp.x << 16); h[1] += __builtin_amdgcn_rcpf(1.f + __expf(-sc * a[1])) * __uint_as_float(pp.x & 0xffff0000u);
;                             h[2] += __builtin_amdgcn_rcpf(1.f + __expf(-sc * a[2])) * __uint_as_float(pp.y << 16); h[3] += __builtin_amdgcn_rcpf(1.f + __expf(-sc * a[3])) * __uint_as_float(pp.y & 0xffff0000u); }
;                         else h = h + a;
;                         s += (h[0] * h[0] + h[1] * h[1]) + (h[2] * h[2] + h[3] * h[3]);
;                         u32x2e o; o.x = cvt_pk_bf16(h[0], h[1]); o.y = cvt_pk_bf16(h[2], h[3]); *(u32x2e*)(Hout + p) = o; }
;                 s += __shfl_xor(s, 16); s += __shfl_xor(s, 32);
;                 if (fq == 0) atomicAdd(rss_out + row, s); }
	v_lshlrev_b32_e32 v198, 16, v180
	v_and_b32_e32 v199, 0xffff0000, v180
	v_lshlrev_b32_e32 v180, 16, v181
	v_and_b32_e32 v181, 0xffff0000, v181
	v_pk_add_f32 v[128:129], v[128:129], v[180:181]
	v_pk_add_f32 v[126:127], v[126:127], v[198:199]
	v_mul_f32_e32 v181, v129, v129
	v_mul_f32_e32 v180, v127, v127
	v_fmac_f32_e32 v180, v126, v126
	v_fmac_f32_e32 v181, v128, v128
	v_cvt_pk_bf16_f32 v126, v126, v127
	v_cvt_pk_bf16_f32 v127, v128, v129
	v_lshl_add_u64 v[128:129], s[48:49], 0, v[140:141]
	v_lshl_add_u64 v[128:129], v[128:129], 0, v[178:179]
	v_bfe_u32 v250, v176, 2, 1
	v_mul_u32_u24_e32 v250, 24, v250
	v_add_u32_e32 v128, v250, v128
	v_mov_b32_e32 v242, v126
	v_mov_b32_e32 v243, v127
	v_lshlrev_b32_e32 v126, 16, v192
	v_and_b32_e32 v127, 0xffff0000, v192
	v_pk_add_f32 v[122:123], v[122:123], v[126:127]
	v_lshlrev_b32_e32 v178, 16, v193
	v_and_b32_e32 v179, 0xffff0000, v193
	v_mul_f32_e32 v126, v123, v123
	v_pk_add_f32 v[124:125], v[124:125], v[178:179]
	v_fmac_f32_e32 v126, v122, v122
	v_cvt_pk_bf16_f32 v122, v122, v123
	v_cvt_pk_bf16_f32 v123, v124, v125
	v_mul_f32_e32 v127, v125, v125
	v_mov_b32_e32 v244, v122
	v_mov_b32_e32 v245, v123
	s_nop 1
	v_permlane16_swap_b32 v242, v244
	v_permlane16_swap_b32 v243, v245
	global_store_dwordx4 v[128:129], v[242:245], off
	v_lshlrev_b32_e32 v122, 16, v194
	v_and_b32_e32 v123, 0xffff0000, v194
	v_fmac_f32_e32 v127, v124, v124
	v_lshlrev_b32_e32 v124, 16, v195
	v_and_b32_e32 v125, 0xffff0000, v195
	v_pk_add_f32 v[118:119], v[118:119], v[122:123]
	v_pk_add_f32 v[120:121], v[120:121], v[124:125]
	v_mul_f32_e32 v122, v119, v119
	v_fmac_f32_e32 v122, v118, v118
	v_mul_f32_e32 v123, v121, v121
	v_cvt_pk_bf16_f32 v118, v118, v119
	v_cvt_pk_bf16_f32 v119, v120, v121
	v_fmac_f32_e32 v123, v120, v120
	v_mov_b32_e32 v242, v118
	v_mov_b32_e32 v243, v119
	v_lshlrev_b32_e32 v118, 16, v196
	v_and_b32_e32 v119, 0xffff0000, v196
	v_lshlrev_b32_e32 v120, 16, v197
	v_and_b32_e32 v121, 0xffff0000, v197
	v_pk_add_f32 v[116:117], v[116:117], v[120:121]
	v_pk_add_f32 v[118:119], v[114:115], v[118:119]
	v_mul_f32_e32 v115, v117, v117
	v_mul_f32_e32 v114, v119, v119
	v_fmac_f32_e32 v114, v118, v118
	v_fmac_f32_e32 v115, v116, v116
	v_cvt_pk_bf16_f32 v118, v118, v119
	v_cvt_pk_bf16_f32 v119, v116, v117
	v_and_b32_e32 v116, 64, v216
	v_add_f32_e32 v180, v180, v181
	v_add_f32_e32 v126, v126, v127
	v_add_f32_e32 v114, v114, v115
	v_xor_b32_e32 v115, 16, v216
	v_add_u32_e32 v117, 64, v116
	v_add_f32_e32 v126, v180, v126
	v_add_f32_e32 v122, v122, v123
	v_cmp_lt_i32_e32 vcc, v115, v117
	v_add_f32_e32 v122, v126, v122
	v_add_f32_e32 v114, v122, v114
	v_cndmask_b32_e32 v115, v216, v115, vcc
	v_lshlrev_b32_e32 v116, 2, v115
	ds_bpermute_b32 v115, v116, v114
	v_mov_b32_e32 v244, v118
	v_mov_b32_e32 v245, v119
	s_nop 1
	v_permlane16_swap_b32 v242, v244
	v_permlane16_swap_b32 v243, v245
	global_store_dwordx4 v[128:129], v[242:245], off offset:256
	s_waitcnt lgkmcnt(0)
	v_add_f32_e32 v118, v114, v115
	v_xor_b32_e32 v114, 32, v216
	v_cmp_lt_i32_e32 vcc, v114, v117
	s_nop 1
	v_cndmask_b32_e32 v114, v216, v114, vcc
	v_lshlrev_b32_e32 v117, 2, v114
	ds_bpermute_b32 v119, v117, v118
	v_lshl_add_u64 v[114:115], v[170:171], 2, s[50:51]
	s_and_saveexec_b64 s[0:1], s[42:43]
	s_cbranch_execz .LBB0_95
	s_waitcnt lgkmcnt(0)
	v_add_f32_e32 v118, v118, v119
	global_atomic_add_f32 v[114:115], v118, off
.LBB0_95:
	s_or_b64 exec, exec, s[0:1]
	v_lshlrev_b32_e32 v118, 16, v172
	s_waitcnt lgkmcnt(0)
	v_and_b32_e32 v119, 0xffff0000, v172
	v_lshlrev_b32_e32 v120, 16, v173
	v_and_b32_e32 v121, 0xffff0000, v173
	v_pk_add_f32 v[112:113], v[112:113], v[120:121]
	v_pk_add_f32 v[110:111], v[110:111], v[118:119]
	v_mul_f32_e32 v119, v113, v113
	v_mul_f32_e32 v118, v111, v111
	v_fmac_f32_e32 v118, v110, v110
	v_fmac_f32_e32 v119, v112, v112
	v_cvt_pk_bf16_f32 v110, v110, v111
	v_cvt_pk_bf16_f32 v111, v112, v113
	v_lshl_add_u64 v[112:113], s[48:49], 0, v[168:169]
	v_lshl_add_u64 v[112:113], v[136:137], 1, v[112:113]
	v_add_f32_e32 v120, v118, v119
	v_add_u32_e32 v112, v250, v112
	v_mov_b32_e32 v242, v110
	v_mov_b32_e32 v243, v111
	v_lshlrev_b32_e32 v110, 16, v166
	v_and_b32_e32 v111, 0xffff0000, v166
	v_lshlrev_b32_e32 v118, 16, v167
	v_and_b32_e32 v119, 0xffff0000, v167
	v_pk_add_f32 v[108:109], v[108:109], v[118:119]
	v_pk_add_f32 v[106:107], v[106:107], v[110:111]
	v_mul_f32_e32 v111, v109, v109
	v_mul_f32_e32 v110, v107, v107
	v_fmac_f32_e32 v110, v106, v106
	v_fmac_f32_e32 v111, v108, v108
	v_add_f32_e32 v110, v110, v111
	v_add_f32_e32 v120, v120, v110
	v_lshlrev_b32_e32 v110, 16, v164
	v_and_b32_e32 v111, 0xffff0000, v164
	v_lshlrev_b32_e32 v118, 16, v165
	v_and_b32_e32 v119, 0xffff0000, v165
	v_pk_add_f32 v[104:105], v[104:105], v[118:119]
	v_pk_add_f32 v[102:103], v[102:103], v[110:111]
	v_cvt_pk_bf16_f32 v106, v106, v107
	v_mul_f32_e32 v110, v105, v105
	v_mul_f32_e32 v107, v103, v103
	v_fmac_f32_e32 v107, v102, v102
	v_fmac_f32_e32 v110, v104, v104
	v_add_f32_e32 v107, v107, v110
	v_lshlrev_b32_e32 v110, 16, v162
	v_and_b32_e32 v111, 0xffff0000, v162
	v_lshlrev_b32_e32 v118, 16, v163
	v_and_b32_e32 v119, 0xffff0000, v163
	v_pk_add_f32 v[100:101], v[100:101], v[118:119]
	v_pk_add_f32 v[110:111], v[98:99], v[110:111]
	v_mul_f32_e32 v99, v101, v101
	v_mul_f32_e32 v98, v111, v111
	v_fmac_f32_e32 v98, v110, v110
	v_fmac_f32_e32 v99, v100, v100
	v_add_f32_e32 v107, v120, v107
	v_add_f32_e32 v98, v98, v99
	v_add_f32_e32 v98, v107, v98
	ds_bpermute_b32 v99, v116, v98
	v_cvt_pk_bf16_f32 v107, v108, v109
	v_mov_b32_e32 v244, v106
	v_mov_b32_e32 v245, v107
	s_nop 1
	v_permlane16_swap_b32 v242, v244
	v_permlane16_swap_b32 v243, v245
	global_store_dwordx4 v[112:113], v[242:245], off
	v_cvt_pk_bf16_f32 v102, v102, v103
	v_cvt_pk_bf16_f32 v103, v104, v105
	s_waitcnt lgkmcnt(0)
	v_add_f32_e32 v98, v98, v99
	ds_bpermute_b32 v99, v117, v98
	v_mov_b32_e32 v242, v102
	v_mov_b32_e32 v243, v103
	v_cvt_pk_bf16_f32 v102, v110, v111
	v_cvt_pk_bf16_f32 v103, v100, v101
	v_mov_b32_e32 v244, v102
	v_mov_b32_e32 v245, v103
	s_nop 1
	v_permlane16_swap_b32 v242, v244
	v_permlane16_swap_b32 v243, v245
	global_store_dwordx4 v[112:113], v[242:245], off offset:256
	s_and_saveexec_b64 s[0:1], s[42:43]
	s_mov_b32 s28, 0xea00000
	s_movk_i32 s29, 0x2000
	s_movk_i32 s30, 0x104
	s_mov_b32 s31, 0x22200000
	s_cbranch_execz .LBB0_97
	s_waitcnt lgkmcnt(0)
	v_add_f32_e32 v98, v98, v99
	global_atomic_add_f32 v[114:115], v98, off offset:64
; __device__ __forceinline__ unsigned cvt_pk_bf16(float lo, float hi) { unsigned r; asm volatile("v_cvt_pk_bf16_f32 %0, %1, %2" : "=v"(r) : "v"(lo), "v"(hi)); return r; }
;     __device__ __forceinline__ void operator()(const f32x4 (&acc)[2][2][4][2], const Unit& u, int wr, int wc, int fr, int fq) const {
;     ...
;             for (int m = 0; m < 4; ++m) { const int row = row0 + ai * HALF + m * 16; const size_t ro = (size_t)row * 2048 + col0;
;                 float sc = 1.f; if (GATE) sc = rsqrtf(scv[m] * (1.f / 2048.f) + 1e-6f);
;                 float s = 0.f;
; #pragma unroll
;                 for (int bj = 0; bj < 2; ++bj)
; #pragma unroll
;                     for (int n = 0; n < 2; ++n) { const size_t p = ro + bj * HALF + n * 16; const u32x2e hh = hw[m][bj][n], pp = pw[m][bj][n]; const f32x4 a = acc[ai][bj][m][n];
;                         f32x4 h; h[0] = __uint_as_float(hh.x << 16); h[1] = __uint_as_float(hh.x & 0xffff0000u); h[2] = __uint_as_float(hh.y << 16); h[3] = __uint_as_float(hh.y & 0xffff0000u);
;                         if (GATE) {
;                             h[0] += __builtin_amdgcn_rcpf(1.f + __expf(-sc * a[0])) * __uint_as_float(pp.x << 16); h[1] += __builtin_amdgcn_rcpf(1.f + __expf(-sc * a[1])) * __uint_as_float(pp.x & 0xffff0000u);
;                             h[2] += __builtin_amdgcn_rcpf(1.f + __expf(-sc * a[2])) * __uint_as_float(pp.y << 16); h[3] += __builtin_amdgcn_rcpf(1.f + __expf(-sc * a[3])) * __uint_as_float(pp.y & 0xffff0000u); }
;                         else h = h + a;
;                         s += (h[0] * h[0] + h[1] * h[1]) + (h[2] * h[2] + h[3] * h[3]);
;                         u32x2e o; o.x = cvt_pk_bf16(h[0], h[1]); o.y = cvt_pk_bf16(h[2], h[3]); *(u32x2e*)(Hout + p) = o; }
;                 s += __shfl_xor(s, 16); s += __shfl_xor(s, 32);
;                 if (fq == 0) atomicAdd(rss_out + row, s); }
.LBB0_97:
	s_or_b64 exec, exec, s[0:1]
	v_lshlrev_b32_e32 v98, 16, v160
	s_waitcnt lgkmcnt(0)
	v_and_b32_e32 v99, 0xffff0000, v160
	v_lshlrev_b32_e32 v100, 16, v161
	v_and_b32_e32 v101, 0xffff0000, v161
	v_pk_add_f32 v[96:97], v[96:97], v[100:101]
	v_pk_add_f32 v[94:95], v[94:95], v[98:99]
	v_mul_f32_e32 v99, v97, v97
	v_mul_f32_e32 v98, v95, v95
	v_fmac_f32_e32 v98, v94, v94
	v_fmac_f32_e32 v99, v96, v96
	v_cvt_pk_bf16_f32 v94, v94, v95
	v_cvt_pk_bf16_f32 v95, v96, v97
	v_lshl_add_u64 v[96:97], s[48:49], 0, v[158:159]
	v_lshl_add_u64 v[96:97], v[136:137], 1, v[96:97]
	v_add_f32_e32 v100, v98, v99
	v_add_u32_e32 v96, v250, v96
	v_mov_b32_e32 v242, v94
	v_mov_b32_e32 v243, v95
	v_lshlrev_b32_e32 v94, 16, v156
	v_and_b32_e32 v95, 0xffff0000, v156
	v_lshlrev_b32_e32 v98, 16, v157
	v_and_b32_e32 v99, 0xffff0000, v157
	v_pk_add_f32 v[92:93], v[92:93], v[98:99]
	v_pk_add_f32 v[90:91], v[90:91], v[94:95]
	v_mul_f32_e32 v95, v93, v93
	v_mul_f32_e32 v94, v91, v91
	v_fmac_f32_e32 v94, v90, v90
	v_fmac_f32_e32 v95, v92, v92
	v_add_f32_e32 v94, v94, v95
	v_add_f32_e32 v100, v100, v94
	v_lshlrev_b32_e32 v94, 16, v152
	v_and_b32_e32 v95, 0xffff0000, v152
	v_lshlrev_b32_e32 v98, 16, v153
	v_and_b32_e32 v99, 0xffff0000, v153
	v_pk_add_f32 v[88:89], v[88:89], v[98:99]
	v_pk_add_f32 v[86:87], v[86:87], v[94:95]
	v_cvt_pk_bf16_f32 v90, v90, v91
	v_mul_f32_e32 v94, v89, v89
	v_mul_f32_e32 v91, v87, v87
	v_fmac_f32_e32 v91, v86, v86
	v_fmac_f32_e32 v94, v88, v88
	v_add_f32_e32 v91, v91, v94
	v_lshlrev_b32_e32 v94, 16, v148
	v_and_b32_e32 v95, 0xffff0000, v148
	v_lshlrev_b32_e32 v98, 16, v149
	v_and_b32_e32 v99, 0xffff0000, v149
	v_pk_add_f32 v[84:85], v[84:85], v[98:99]
	v_pk_add_f32 v[94:95], v[82:83], v[94:95]
	v_mul_f32_e32 v83, v85, v85
	v_mul_f32_e32 v82, v95, v95
	v_fmac_f32_e32 v82, v94, v94
	v_fmac_f32_e32 v83, v84, v84
	v_add_f32_e32 v91, v100, v91
	v_add_f32_e32 v82, v82, v83
	v_add_f32_e32 v82, v91, v82
	ds_bpermute_b32 v83, v116, v82
	v_cvt_pk_bf16_f32 v91, v92, v93
	v_mov_b32_e32 v244, v90
	v_mov_b32_e32 v245, v91
	s_nop 1
	v_permlane16_swap_b32 v242, v244
	v_permlane16_swap_b32 v243, v245
	global_store_dwordx4 v[96:97], v[242:245], off
	v_cvt_pk_bf16_f32 v86, v86, v87
	v_cvt_pk_bf16_f32 v87, v88, v89
	s_waitcnt lgkmcnt(0)
	v_add_f32_e32 v82, v82, v83
	ds_bpermute_b32 v83, v117, v82
	v_mov_b32_e32 v242, v86
	v_mov_b32_e32 v243, v87
	v_cvt_pk_bf16_f32 v86, v94, v95
	v_cvt_pk_bf16_f32 v87, v84, v85
	v_mov_b32_e32 v244, v86
	v_mov_b32_e32 v245, v87
	s_nop 1
	v_permlane16_swap_b32 v242, v244
	v_permlane16_swap_b32 v243, v245
	global_store_dwordx4 v[96:97], v[242:245], off offset:256
	s_and_saveexec_b64 s[0:1], s[42:43]
	s_cbranch_execz .LBB0_99
	s_waitcnt lgkmcnt(0)
	v_add_f32_e32 v82, v82, v83
	global_atomic_add_f32 v[114:115], v82, off offset:128
.LBB0_99:
	s_or_b64 exec, exec, s[0:1]
	v_lshlrev_b32_e32 v82, 16, v154
	s_waitcnt lgkmcnt(0)
	v_and_b32_e32 v83, 0xffff0000, v154
	v_lshlrev_b32_e32 v84, 16, v155
	v_and_b32_e32 v85, 0xffff0000, v155
	v_pk_add_f32 v[80:81], v[80:81], v[84:85]
	v_pk_add_f32 v[78:79], v[78:79], v[82:83]
	v_mul_f32_e32 v83, v81, v81
	v_mul_f32_e32 v82, v79, v79
	v_fmac_f32_e32 v82, v78, v78
	v_fmac_f32_e32 v83, v80, v80
	v_cvt_pk_bf16_f32 v78, v78, v79
	v_cvt_pk_bf16_f32 v79, v80, v81
	v_lshl_add_u64 v[80:81], s[48:49], 0, v[144:145]
	v_lshl_add_u64 v[80:81], v[136:137], 1, v[80:81]
	v_add_f32_e32 v84, v82, v83
	v_add_u32_e32 v80, v250, v80
	v_mov_b32_e32 v242, v78
	v_mov_b32_e32 v243, v79
	v_lshlrev_b32_e32 v78, 16, v150
	v_and_b32_e32 v79, 0xffff0000, v150
	v_lshlrev_b32_e32 v82, 16, v151
	v_and_b32_e32 v83, 0xffff0000, v151
	v_pk_add_f32 v[76:77], v[76:77], v[82:83]
	v_pk_add_f32 v[74:75], v[74:75], v[78:79]
	v_mul_f32_e32 v79, v77, v77
	v_mul_f32_e32 v78, v75, v75
	v_fmac_f32_e32 v78, v74, v74
	v_fmac_f32_e32 v79, v76, v76
	v_add_f32_e32 v78, v78, v79
	v_add_f32_e32 v84, v84, v78
	v_lshlrev_b32_e32 v78, 16, v146
	v_and_b32_e32 v79, 0xffff0000, v146
	v_lshlrev_b32_e32 v82, 16, v147
	v_and_b32_e32 v83, 0xffff0000, v147
	v_pk_add_f32 v[72:73], v[72:73], v[82:83]
	v_pk_add_f32 v[70:71], v[70:71], v[78:79]
	v_cvt_pk_bf16_f32 v74, v74, v75
	v_mul_f32_e32 v78, v73, v73
	v_mul_f32_e32 v75, v71, v71
	v_fmac_f32_e32 v75, v70, v70
	v_fmac_f32_e32 v78, v72, v72
	v_add_f32_e32 v75, v75, v78
	v_lshlrev_b32_e32 v78, 16, v142
	v_and_b32_e32 v79, 0xffff0000, v142
	v_lshlrev_b32_e32 v82, 16, v143
	v_and_b32_e32 v83, 0xffff0000, v143
	v_pk_add_f32 v[68:69], v[68:69], v[82:83]
	v_pk_add_f32 v[78:79], v[66:67], v[78:79]
	v_mul_f32_e32 v67, v69, v69
	v_mul_f32_e32 v66, v79, v79
	v_fmac_f32_e32 v66, v78, v78
	v_fmac_f32_e32 v67, v68, v68
	v_add_f32_e32 v75, v84, v75
	v_add_f32_e32 v66, v66, v67
	v_add_f32_e32 v66, v75, v66
	ds_bpermute_b32 v67, v116, v66
	v_cvt_pk_bf16_f32 v75, v76, v77
	v_mov_b32_e32 v244, v74
	v_mov_b32_e32 v245, v75
	s_nop 1
	v_permlane16_swap_b32 v242, v244
	v_permlane16_swap_b32 v243, v245
	global_store_dwordx4 v[80:81], v[242:245], off
	v_cvt_pk_bf16_f32 v70, v70, v71
	v_cvt_pk_bf16_f32 v71, v72, v73
	s_waitcnt lgkmcnt(0)
	v_add_f32_e32 v66, v66, v67
	ds_bpermute_b32 v67, v117, v66
	v_mov_b32_e32 v242, v70
	v_mov_b32_e32 v243, v71
	v_cvt_pk_bf16_f32 v70, v78, v79
	v_cvt_pk_bf16_f32 v71, v68, v69
	v_mov_b32_e32 v244, v70
	v_mov_b32_e32 v245, v71
	s_nop 1
	v_permlane16_swap_b32 v242, v244
	v_permlane16_swap_b32 v243, v245
	global_store_dwordx4 v[80:81], v[242:245], off offset:256
	s_and_saveexec_b64 s[0:1], s[42:43]
	s_cbranch_execz .LBB0_101
	s_waitcnt lgkmcnt(0)
	v_add_f32_e32 v66, v66, v67
	global_atomic_add_f32 v[114:115], v66, off offset:192
; __device__ __forceinline__ unsigned cvt_pk_bf16(float lo, float hi) { unsigned r; asm volatile("v_cvt_pk_bf16_f32 %0, %1, %2" : "=v"(r) : "v"(lo), "v"(hi)); return r; }
;     __device__ __forceinline__ void operator()(const f32x4 (&acc)[2][2][4][2], const Unit& u, int wr, int wc, int fr, int fq) const {
;     ...
;             for (int m = 0; m < 4; ++m) { const int row = row0 + ai * HALF + m * 16; const size_t ro = (size_t)row * 2048 + col0;
;                 scv[m] = GATE ? rss_in[row] : 0.f;
; #pragma unroll
;                 for (int bj = 0; bj < 2; ++bj)
; #pragma unroll
;                     for (int n = 0; n < 2; ++n) { const size_t p = ro + bj * HALF + n * 16; hw[m][bj][n] = *(const u32x2e*)(Hin + p); if (GATE) pw[m][bj][n] = *(const u32x2e*)(PP + p); else pw[m][bj][n] = (u32x2e){0u, 0u}; } }
; #pragma unroll
;             for (int m = 0; m < 4; ++m) { const int row = row0 + ai * HALF + m * 16; const size_t ro = (size_t)row * 2048 + col0;
;                 float sc = 1.f; if (GATE) sc = rsqrtf(scv[m] * (1.f / 2048.f) + 1e-6f);
;                 float s = 0.f;
; #pragma unroll
;                 for (int bj = 0; bj < 2; ++bj)
; #pragma unroll
;                     for (int n = 0; n < 2; ++n) { const size_t p = ro + bj * HALF + n * 16; const u32x2e hh = hw[m][bj][n], pp = pw[m][bj][n]; const f32x4 a = acc[ai][bj][m][n];
;                         f32x4 h; h[0] = __uint_as_float(hh.x << 16); h[1] = __uint_as_float(hh.x & 0xffff0000u); h[2] = __uint_as_float(hh.y << 16); h[3] = __uint_as_float(hh.y & 0xffff0000u);
;                         if (GATE) {
;                             h[0] += __builtin_amdgcn_rcpf(1.f + __expf(-sc * a[0])) * __uint_as_float(pp.x << 16); h[1] += __builtin_amdgcn_rcpf(1.f + __expf(-sc * a[1])) * __uint_as_float(pp.x & 0xffff0000u);
;                             h[2] += __builtin_amdgcn_rcpf(1.f + __expf(-sc * a[2])) * __uint_as_float(pp.y << 16); h[3] += __builtin_amdgcn_rcpf(1.f + __expf(-sc * a[3])) * __uint_as_float(pp.y & 0xffff0000u); }
;                         else h = h + a;
;                         s += (h[0] * h[0] + h[1] * h[1]) + (h[2] * h[2] + h[3] * h[3]);
;                         u32x2e o; o.x = cvt_pk_bf16(h[0], h[1]); o.y = cvt_pk_bf16(h[2], h[3]); *(u32x2e*)(Hout + p) = o; }
;                 s += __shfl_xor(s, 16); s += __shfl_xor(s, 32);
;                 if (fq == 0) atomicAdd(rss_out + row, s); }
.LBB0_101:
	s_or_b64 exec, exec, s[0:1]
	s_waitcnt vmcnt(8)
	s_barrier
	s_mov_b64 s[0:1], 0x80000
	v_lshl_add_u64 v[100:101], v[140:141], 0, s[0:1]
	s_waitcnt lgkmcnt(0)
	v_lshl_add_u64 v[66:67], v[138:139], 0, v[100:101]
	ds_read_b64 v[102:103], v130 offset:0
	ds_read_b64 v[104:105], v131 offset:0
	ds_read_b64 v[98:99], v130 offset:256
	ds_read_b64 v[96:97], v131 offset:256
	s_mov_b64 s[0:1], 0x90000
	v_lshl_add_u64 v[92:93], v[140:141], 0, s[0:1]
	s_mov_b64 s[0:1], 0xa0000
	v_lshl_add_u64 v[66:67], v[138:139], 0, v[92:93]
	v_lshl_add_u64 v[82:83], v[140:141], 0, s[0:1]
	s_mov_b64 s[0:1], 0xb0000
	ds_read_b64 v[94:95], v130 offset:8192
	ds_read_b64 v[90:91], v131 offset:8192
	ds_read_b64 v[88:89], v130 offset:8448
	ds_read_b64 v[86:87], v131 offset:8448
	v_lshl_add_u64 v[66:67], v[138:139], 0, v[82:83]
	v_lshl_add_u64 v[68:69], v[140:141], 0, s[0:1]
	ds_read_b64 v[84:85], v130 offset:16384
	ds_read_b64 v[80:81], v131 offset:16384
	ds_read_b64 v[78:79], v130 offset:16640
	ds_read_b64 v[74:75], v131 offset:16640
	v_lshl_add_u64 v[66:67], v[138:139], 0, v[68:69]
	ds_read_b64 v[76:77], v130 offset:24576
	ds_read_b64 v[72:73], v131 offset:24576
	ds_read_b64 v[70:71], v130 offset:24832
	s_nop 0
	ds_read_b64 v[66:67], v131 offset:24832
	s_waitcnt vmcnt(0) lgkmcnt(0)
	s_waitcnt vmcnt(15)
	v_lshlrev_b32_e32 v106, 16, v102
	v_and_b32_e32 v107, 0xffff0000, v102
	v_lshlrev_b32_e32 v102, 16, v103
	v_and_b32_e32 v103, 0xffff0000, v103
	v_pk_add_f32 v[64:65], v[64:65], v[102:103]
	v_pk_add_f32 v[62:63], v[62:63], v[106:107]
	v_mul_f32_e32 v103, v65, v65
	v_mul_f32_e32 v102, v63, v63
	v_fmac_f32_e32 v102, v62, v62
	v_fmac_f32_e32 v103, v64, v64
	v_add_f32_e32 v106, v102, v103
	v_cvt_pk_bf16_f32 v102, v62, v63
	v_cvt_pk_bf16_f32 v103, v64, v65
	s_waitcnt vmcnt(14)
	v_lshlrev_b32_e32 v64, 16, v104
	v_and_b32_e32 v65, 0xffff0000, v104
	v_lshl_add_u64 v[62:63], s[48:49], 0, v[100:101]
	v_pk_add_f32 v[58:59], v[58:59], v[64:65]
	v_lshl_add_u64 v[62:63], v[136:137], 1, v[62:63]
	v_lshlrev_b32_e32 v100, 16, v105
	v_and_b32_e32 v101, 0xffff0000, v105
	v_mul_f32_e32 v64, v59, v59
	v_add_u32_e32 v62, v250, v62
	v_mov_b32_e32 v242, v102
	v_mov_b32_e32 v243, v103
	v_pk_add_f32 v[60:61], v[60:61], v[100:101]
	v_fmac_f32_e32 v64, v58, v58
	v_cvt_pk_bf16_f32 v58, v58, v59
	v_cvt_pk_bf16_f32 v59, v60, v61
	v_mul_f32_e32 v65, v61, v61
	v_mov_b32_e32 v244, v58
	v_mov_b32_e32 v245, v59
	s_nop 1
	v_permlane16_swap_b32 v242, v244
	v_permlane16_swap_b32 v243, v245
	global_store_dwordx4 v[62:63], v[242:245], off
	s_waitcnt vmcnt(15)
	v_lshlrev_b32_e32 v58, 16, v98
	v_and_b32_e32 v59, 0xffff0000, v98
	v_fmac_f32_e32 v65, v60, v60
	v_lshlrev_b32_e32 v60, 16, v99
	v_and_b32_e32 v61, 0xffff0000, v99
	v_pk_add_f32 v[54:55], v[54:55], v[58:59]
	v_pk_add_f32 v[56:57], v[56:57], v[60:61]
	v_mul_f32_e32 v58, v55, v55
	v_fmac_f32_e32 v58, v54, v54
	v_mul_f32_e32 v59, v57, v57
	v_cvt_pk_bf16_f32 v54, v54, v55
	v_cvt_pk_bf16_f32 v55, v56, v57
	v_fmac_f32_e32 v59, v56, v56
	v_mov_b32_e32 v242, v54
	v_mov_b32_e32 v243, v55
	s_waitcnt vmcnt(15)
	v_lshlrev_b32_e32 v54, 16, v96
	v_and_b32_e32 v55, 0xffff0000, v96
	v_lshlrev_b32_e32 v56, 16, v97
	v_and_b32_e32 v57, 0xffff0000, v97
	v_pk_add_f32 v[52:53], v[52:53], v[56:57]
	v_pk_add_f32 v[50:51], v[50:51], v[54:55]
	v_add_f32_e32 v64, v64, v65
	v_mul_f32_e32 v54, v51, v51
	v_mul_f32_e32 v55, v53, v53
	v_add_f32_e32 v64, v106, v64
	v_add_f32_e32 v58, v58, v59
	v_fmac_f32_e32 v54, v50, v50
	v_fmac_f32_e32 v55, v52, v52
	v_add_f32_e32 v58, v64, v58
	v_add_f32_e32 v54, v54, v55
	v_add_f32_e32 v54, v58, v54
	v_cvt_pk_bf16_f32 v50, v50, v51
	v_cvt_pk_bf16_f32 v51, v52, v53
	v_mov_b32_e32 v244, v50
	v_mov_b32_e32 v245, v51
	s_nop 1
	v_permlane16_swap_b32 v242, v244
	v_permlane16_swap_b32 v243, v245
	global_store_dwordx4 v[62:63], v[242:245], off offset:256
	ds_bpermute_b32 v50, v116, v54
	s_waitcnt lgkmcnt(0)
	v_add_f32_e32 v50, v54, v50
	ds_bpermute_b32 v51, v117, v50
	s_and_saveexec_b64 s[0:1], s[42:43]
	s_cbranch_execz .LBB0_103
	s_waitcnt lgkmcnt(0)
	v_add_f32_e32 v50, v50, v51
	global_atomic_add_f32 v[114:115], v50, off offset:512
.LBB0_103:
	s_or_b64 exec, exec, s[0:1]
	s_waitcnt vmcnt(15)
	v_lshlrev_b32_e32 v50, 16, v94
	s_waitcnt lgkmcnt(0)
	v_and_b32_e32 v51, 0xffff0000, v94
	v_lshlrev_b32_e32 v52, 16, v95
	v_and_b32_e32 v53, 0xffff0000, v95
	v_pk_add_f32 v[48:49], v[48:49], v[52:53]
	v_pk_add_f32 v[46:47], v[46:47], v[50:51]
	v_mul_f32_e32 v51, v49, v49
	v_mul_f32_e32 v50, v47, v47
	v_fmac_f32_e32 v50, v46, v46
	v_fmac_f32_e32 v51, v48, v48
	v_cvt_pk_bf16_f32 v46, v46, v47
	v_cvt_pk_bf16_f32 v47, v48, v49
	v_lshl_add_u64 v[48:49], s[48:49], 0, v[92:93]
	v_lshl_add_u64 v[48:49], v[136:137], 1, v[48:49]
	v_add_f32_e32 v52, v50, v51
	v_add_u32_e32 v48, v250, v48
	v_mov_b32_e32 v242, v46
	v_mov_b32_e32 v243, v47
	s_waitcnt vmcnt(15)
	v_lshlrev_b32_e32 v46, 16, v90
	v_and_b32_e32 v47, 0xffff0000, v90
	v_lshlrev_b32_e32 v50, 16, v91
	v_and_b32_e32 v51, 0xffff0000, v91
	v_pk_add_f32 v[44:45], v[44:45], v[50:51]
	v_pk_add_f32 v[42:43], v[42:43], v[46:47]
	v_mul_f32_e32 v47, v45, v45
	v_mul_f32_e32 v46, v43, v43
	v_fmac_f32_e32 v46, v42, v42
	v_fmac_f32_e32 v47, v44, v44
	v_add_f32_e32 v46, v46, v47
	v_add_f32_e32 v52, v52, v46
	s_waitcnt vmcnt(14)
	v_lshlrev_b32_e32 v46, 16, v88
	v_and_b32_e32 v47, 0xffff0000, v88
	v_lshlrev_b32_e32 v50, 16, v89
	v_and_b32_e32 v51, 0xffff0000, v89
	v_pk_add_f32 v[40:41], v[40:41], v[50:51]
	v_pk_add_f32 v[38:39], v[38:39], v[46:47]
	v_cvt_pk_bf16_f32 v42, v42, v43
	v_mul_f32_e32 v46, v41, v41
	v_mul_f32_e32 v43, v39, v39
	v_fmac_f32_e32 v43, v38, v38
	v_fmac_f32_e32 v46, v40, v40
	v_add_f32_e32 v43, v43, v46
	s_waitcnt vmcnt(13)
	v_lshlrev_b32_e32 v46, 16, v86
	v_and_b32_e32 v47, 0xffff0000, v86
	v_lshlrev_b32_e32 v50, 16, v87
	v_and_b32_e32 v51, 0xffff0000, v87
	v_pk_add_f32 v[36:37], v[36:37], v[50:51]
	v_pk_add_f32 v[46:47], v[34:35], v[46:47]
	v_mul_f32_e32 v35, v37, v37
	v_mul_f32_e32 v34, v47, v47
	v_fmac_f32_e32 v34, v46, v46
	v_fmac_f32_e32 v35, v36, v36
	v_add_f32_e32 v43, v52, v43
	v_add_f32_e32 v34, v34, v35
	v_add_f32_e32 v34, v43, v34
	ds_bpermute_b32 v35, v116, v34
	v_cvt_pk_bf16_f32 v43, v44, v45
	v_mov_b32_e32 v244, v42
	v_mov_b32_e32 v245, v43
	s_nop 1
	v_permlane16_swap_b32 v242, v244
	v_permlane16_swap_b32 v243, v245
	global_store_dwordx4 v[48:49], v[242:245], off
	v_cvt_pk_bf16_f32 v38, v38, v39
	v_cvt_pk_bf16_f32 v39, v40, v41
	s_waitcnt lgkmcnt(0)
	v_add_f32_e32 v34, v34, v35
	ds_bpermute_b32 v35, v117, v34
	v_mov_b32_e32 v242, v38
	v_mov_b32_e32 v243, v39
	v_cvt_pk_bf16_f32 v38, v46, v47
	v_cvt_pk_bf16_f32 v39, v36, v37
	v_mov_b32_e32 v244, v38
	v_mov_b32_e32 v245, v39
	s_nop 1
	v_permlane16_swap_b32 v242, v244
	v_permlane16_swap_b32 v243, v245
	global_store_dwordx4 v[48:49], v[242:245], off offset:256
	s_and_saveexec_b64 s[0:1], s[42:43]
	s_cbranch_execz .LBB0_105
	s_waitcnt lgkmcnt(0)
	v_add_f32_e32 v34, v34, v35
	global_atomic_add_f32 v[114:115], v34, off offset:576
; __device__ __forceinline__ unsigned cvt_pk_bf16(float lo, float hi) { unsigned r; asm volatile("v_cvt_pk_bf16_f32 %0, %1, %2" : "=v"(r) : "v"(lo), "v"(hi)); return r; }
;     __device__ __forceinline__ void operator()(const f32x4 (&acc)[2][2][4][2], const Unit& u, int wr, int wc, int fr, int fq) const {
;     ...
;             for (int m = 0; m < 4; ++m) { const int row = row0 + ai * HALF + m * 16; const size_t ro = (size_t)row * 2048 + col0;
;                 float sc = 1.f; if (GATE) sc = rsqrtf(scv[m] * (1.f / 2048.f) + 1e-6f);
;                 float s = 0.f;
; #pragma unroll
;                 for (int bj = 0; bj < 2; ++bj)
; #pragma unroll
;                     for (int n = 0; n < 2; ++n) { const size_t p = ro + bj * HALF + n * 16; const u32x2e hh = hw[m][bj][n], pp = pw[m][bj][n]; const f32x4 a = acc[ai][bj][m][n];
;                         f32x4 h; h[0] = __uint_as_float(hh.x << 16); h[1] = __uint_as_float(hh.x & 0xffff0000u); h[2] = __uint_as_float(hh.y << 16); h[3] = __uint_as_float(hh.y & 0xffff0000u);
;                         if (GATE) {
;                             h[0] += __builtin_amdgcn_rcpf(1.f + __expf(-sc * a[0])) * __uint_as_float(pp.x << 16); h[1] += __builtin_amdgcn_rcpf(1.f + __expf(-sc * a[1])) * __uint_as_float(pp.x & 0xffff0000u);
;                             h[2] += __builtin_amdgcn_rcpf(1.f + __expf(-sc * a[2])) * __uint_as_float(pp.y << 16); h[3] += __builtin_amdgcn_rcpf(1.f + __expf(-sc * a[3])) * __uint_as_float(pp.y & 0xffff0000u); }
;                         else h = h + a;
;                         s += (h[0] * h[0] + h[1] * h[1]) + (h[2] * h[2] + h[3] * h[3]);
;                         u32x2e o; o.x = cvt_pk_bf16(h[0], h[1]); o.y = cvt_pk_bf16(h[2], h[3]); *(u32x2e*)(Hout + p) = o; }
;                 s += __shfl_xor(s, 16); s += __shfl_xor(s, 32);
;                 if (fq == 0) atomicAdd(rss_out + row, s); }
.LBB0_105:
	s_or_b64 exec, exec, s[0:1]
	s_waitcnt vmcnt(15)
	v_lshlrev_b32_e32 v34, 16, v84
	s_waitcnt lgkmcnt(0)
	v_and_b32_e32 v35, 0xffff0000, v84
	v_lshlrev_b32_e32 v36, 16, v85
	v_and_b32_e32 v37, 0xffff0000, v85
	v_pk_add_f32 v[32:33], v[32:33], v[36:37]
	v_pk_add_f32 v[30:31], v[30:31], v[34:35]
	v_mul_f32_e32 v35, v33, v33
	v_mul_f32_e32 v34, v31, v31
	v_fmac_f32_e32 v34, v30, v30
	v_fmac_f32_e32 v35, v32, v32
	v_cvt_pk_bf16_f32 v30, v30, v31
	v_cvt_pk_bf16_f32 v31, v32, v33
	v_lshl_add_u64 v[32:33], s[48:49], 0, v[82:83]
	v_lshl_add_u64 v[32:33], v[136:137], 1, v[32:33]
	v_add_f32_e32 v36, v34, v35
	v_add_u32_e32 v32, v250, v32
	v_mov_b32_e32 v242, v30
	v_mov_b32_e32 v243, v31
	s_waitcnt vmcnt(15)
	v_lshlrev_b32_e32 v30, 16, v80
	v_and_b32_e32 v31, 0xffff0000, v80
	v_lshlrev_b32_e32 v34, 16, v81
	v_and_b32_e32 v35, 0xffff0000, v81
	v_pk_add_f32 v[28:29], v[28:29], v[34:35]
	v_pk_add_f32 v[26:27], v[26:27], v[30:31]
	v_mul_f32_e32 v31, v29, v29
	v_mul_f32_e32 v30, v27, v27
	v_fmac_f32_e32 v30, v26, v26
	v_fmac_f32_e32 v31, v28, v28
	v_add_f32_e32 v30, v30, v31
	v_add_f32_e32 v36, v36, v30
	s_waitcnt vmcnt(14)
	v_lshlrev_b32_e32 v30, 16, v78
	v_and_b32_e32 v31, 0xffff0000, v78
	v_lshlrev_b32_e32 v34, 16, v79
	v_and_b32_e32 v35, 0xffff0000, v79
	v_pk_add_f32 v[24:25], v[24:25], v[34:35]
	v_pk_add_f32 v[22:23], v[22:23], v[30:31]
	v_cvt_pk_bf16_f32 v26, v26, v27
	v_mul_f32_e32 v30, v25, v25
	v_mul_f32_e32 v27, v23, v23
	v_fmac_f32_e32 v27, v22, v22
	v_fmac_f32_e32 v30, v24, v24
	v_add_f32_e32 v27, v27, v30
	s_waitcnt vmcnt(13)
	v_lshlrev_b32_e32 v30, 16, v74
	v_and_b32_e32 v31, 0xffff0000, v74
	v_lshlrev_b32_e32 v34, 16, v75
	v_and_b32_e32 v35, 0xffff0000, v75
	v_pk_add_f32 v[20:21], v[20:21], v[34:35]
	v_pk_add_f32 v[30:31], v[18:19], v[30:31]
	v_mul_f32_e32 v19, v21, v21
	v_mul_f32_e32 v18, v31, v31
	v_fmac_f32_e32 v18, v30, v30
	v_fmac_f32_e32 v19, v20, v20
	v_add_f32_e32 v27, v36, v27
	v_add_f32_e32 v18, v18, v19
	v_add_f32_e32 v18, v27, v18
	ds_bpermute_b32 v19, v116, v18
	v_cvt_pk_bf16_f32 v27, v28, v29
	v_mov_b32_e32 v244, v26
	v_mov_b32_e32 v245, v27
	s_nop 1
	v_permlane16_swap_b32 v242, v244
	v_permlane16_swap_b32 v243, v245
	global_store_dwordx4 v[32:33], v[242:245], off
	v_cvt_pk_bf16_f32 v22, v22, v23
	v_cvt_pk_bf16_f32 v23, v24, v25
	s_waitcnt lgkmcnt(0)
	v_add_f32_e32 v18, v18, v19
	ds_bpermute_b32 v19, v117, v18
	v_mov_b32_e32 v242, v22
	v_mov_b32_e32 v243, v23
	v_cvt_pk_bf16_f32 v22, v30, v31
	v_cvt_pk_bf16_f32 v23, v20, v21
	v_mov_b32_e32 v244, v22
	v_mov_b32_e32 v245, v23
	s_nop 1
	v_permlane16_swap_b32 v242, v244
	v_permlane16_swap_b32 v243, v245
	global_store_dwordx4 v[32:33], v[242:245], off offset:256
	s_and_saveexec_b64 s[0:1], s[42:43]
	s_cbranch_execz .LBB0_107
	s_waitcnt lgkmcnt(0)
	v_add_f32_e32 v18, v18, v19
	global_atomic_add_f32 v[114:115], v18, off offset:640
.LBB0_107:
	s_or_b64 exec, exec, s[0:1]
	s_waitcnt vmcnt(15)
	v_lshlrev_b32_e32 v18, 16, v76
	s_waitcnt lgkmcnt(0)
	v_and_b32_e32 v19, 0xffff0000, v76
	v_lshlrev_b32_e32 v20, 16, v77
	v_and_b32_e32 v21, 0xffff0000, v77
	v_pk_add_f32 v[16:17], v[16:17], v[20:21]
	v_pk_add_f32 v[14:15], v[14:15], v[18:19]
	v_mul_f32_e32 v19, v17, v17
	v_mul_f32_e32 v18, v15, v15
	v_fmac_f32_e32 v18, v14, v14
	v_fmac_f32_e32 v19, v16, v16
	v_cvt_pk_bf16_f32 v14, v14, v15
	v_cvt_pk_bf16_f32 v15, v16, v17
	v_lshl_add_u64 v[16:17], s[48:49], 0, v[68:69]
	v_lshl_add_u64 v[16:17], v[136:137], 1, v[16:17]
	v_add_f32_e32 v20, v18, v19
	v_add_u32_e32 v16, v250, v16
	v_mov_b32_e32 v242, v14
	v_mov_b32_e32 v243, v15
	s_waitcnt vmcnt(15)
	v_lshlrev_b32_e32 v14, 16, v72
	v_and_b32_e32 v15, 0xffff0000, v72
	v_lshlrev_b32_e32 v18, 16, v73
	v_and_b32_e32 v19, 0xffff0000, v73
	v_pk_add_f32 v[12:13], v[12:13], v[18:19]
	v_pk_add_f32 v[10:11], v[10:11], v[14:15]
	v_mul_f32_e32 v15, v13, v13
	v_mul_f32_e32 v14, v11, v11
	v_fmac_f32_e32 v14, v10, v10
	v_fmac_f32_e32 v15, v12, v12
	v_add_f32_e32 v14, v14, v15
	v_add_f32_e32 v20, v20, v14
	s_waitcnt vmcnt(14)
	v_lshlrev_b32_e32 v14, 16, v70
	v_and_b32_e32 v15, 0xffff0000, v70
	v_lshlrev_b32_e32 v18, 16, v71
	v_and_b32_e32 v19, 0xffff0000, v71
	v_pk_add_f32 v[8:9], v[8:9], v[18:19]
	v_pk_add_f32 v[6:7], v[6:7], v[14:15]
	v_cvt_pk_bf16_f32 v10, v10, v11
	v_mul_f32_e32 v14, v9, v9
	v_mul_f32_e32 v11, v7, v7
	v_fmac_f32_e32 v11, v6, v6
	v_fmac_f32_e32 v14, v8, v8
	v_add_f32_e32 v11, v11, v14
	s_waitcnt vmcnt(13)
	v_lshlrev_b32_e32 v14, 16, v66
	v_and_b32_e32 v15, 0xffff0000, v66
	v_lshlrev_b32_e32 v18, 16, v67
	v_and_b32_e32 v19, 0xffff0000, v67
	v_pk_add_f32 v[4:5], v[4:5], v[18:19]
	v_pk_add_f32 v[14:15], v[2:3], v[14:15]
	v_mul_f32_e32 v3, v5, v5
	v_mul_f32_e32 v2, v15, v15
	v_fmac_f32_e32 v2, v14, v14
	v_fmac_f32_e32 v3, v4, v4
	v_add_f32_e32 v11, v20, v11
	v_add_f32_e32 v2, v2, v3
	v_add_f32_e32 v2, v11, v2
	ds_bpermute_b32 v3, v116, v2
	v_cvt_pk_bf16_f32 v11, v12, v13
	v_mov_b32_e32 v244, v10
	v_mov_b32_e32 v245, v11
	s_nop 1
	v_permlane16_swap_b32 v242, v244
	v_permlane16_swap_b32 v243, v245
	global_store_dwordx4 v[16:17], v[242:245], off
	v_cvt_pk_bf16_f32 v6, v6, v7
	v_cvt_pk_bf16_f32 v7, v8, v9
	s_waitcnt lgkmcnt(0)
	v_add_f32_e32 v2, v2, v3
	ds_bpermute_b32 v3, v117, v2
	v_mov_b32_e32 v242, v6
	v_mov_b32_e32 v243, v7
	v_cvt_pk_bf16_f32 v6, v14, v15
	v_cvt_pk_bf16_f32 v7, v4, v5
	v_mov_b32_e32 v244, v6
	v_mov_b32_e32 v245, v7
	s_nop 1
	v_permlane16_swap_b32 v242, v244
	v_permlane16_swap_b32 v243, v245
	global_store_dwordx4 v[16:17], v[242:245], off offset:256
	s_and_saveexec_b64 s[0:1], s[42:43]
	s_cbranch_execz .LBB0_84
	s_waitcnt lgkmcnt(0)
	v_add_f32_e32 v2, v2, v3
	global_atomic_add_f32 v[114:115], v2, off offset:704
	s_branch .LBB0_84
